# RG-LRU sigmoids: (x+bias)*(-log2e) fused into one fma with pre-scaled bias (250 of 256 sites), still f32
# speedup vs baseline: 1.0072x; 1.0053x over previous
; #define LAS __attribute__((address_space(3)))
; __device__ __forceinline__ float fsig(float x) { return __builtin_amdgcn_rcpf(1.0f + __expf(-x)); }
; template <bool PASS2>
; __device__ __forceinline__ void lru_item(const Frame& F, const Args& a, int item) {
;     ...
;                 for (int ks = 0; ks < 4; ++ks) { const bf16x8 xf = *(const LAS bf16x8*)(AT + (64 * s + 16 * rt + fr) * AT_PITCH + 64 * ks + 16 * fq);
;                     ar[rt] = __builtin_amdgcn_mfma_f32_16x16x32_bf16(xf, wrf[ks], ar[rt], 0, 0, 0); ai[rt] = __builtin_amdgcn_mfma_f32_16x16x32_bf16(xf, wif[ks], ai[rt], 0, 0, 0);
;                     if (ks == ks0) ax[rt] = __builtin_amdgcn_mfma_f32_16x16x32_bf16(xf, sel, ax[rt], 0, 0, 0); } }
;             const int tl0 = 64 * s + 16 * fq;
;             float A16 = 1.f, B16 = 0.f;
; #pragma unroll
;             for (int e = 0; e < 16; ++e) { const int ee = dir ? 15 - e : e; const int rt = ee >> 2, j = ee & 3;
;                 const float rg = fsig(ar[rt][j] + ba), ig = fsig(ai[rt][j] + bi); const float la = logu * rg; const float av = __expf(la);
.LBB0_150:
	s_mov_b32 s100, 0xbfb8aa3b
	v_mul_f32_e32 v181, 0xbfb8aa3b, v128
	v_mul_f32_e32 v190, 0xbfb8aa3b, v130
	v_add_u32_e32 v107, v132, v93
	v_add_u32_e32 v193, 0x11400, v107
	ds_read_b128 v[194:197], v193
	ds_read_b128 v[198:201], v193 offset:64
	ds_read_b128 v[202:205], v193 offset:128
	ds_read_b128 v[206:209], v193 offset:192
	ds_read_b128 v[210:213], v193 offset:4352
	ds_read_b128 v[214:217], v193 offset:4416
	ds_read_b128 v[218:221], v193 offset:4480
	ds_read_b128 v[222:225], v193 offset:4544
	ds_read_b128 v[226:229], v193 offset:8704
	ds_read_b128 v[248:251], v193 offset:8768
	ds_read_b128 v[252:255], v193 offset:8832
	v_cndmask_b32_e64 v40, 0, 1, s[2:3]
	v_cmp_ne_u32_e64 s[10:11], 1, v40
	s_mov_b32 s14, s12
	s_mov_b32 s15, s12
	s_mov_b32 s13, s12
	v_mov_b64_e32 v[66:67], s[14:15]
	v_mov_b64_e32 v[64:65], s[12:13]
	s_andn2_b64 vcc, exec, s[2:3]
	s_waitcnt vmcnt(9) lgkmcnt(10)
	v_mfma_f32_16x16x32_bf16 v[44:47], v[194:197], v[4:7], 0
	s_waitcnt vmcnt(3)
	v_mfma_f32_16x16x32_bf16 v[40:43], v[194:197], v[20:23], 0
	s_cbranch_vccnz .LBB0_152
	v_mfma_f32_16x16x32_bf16 v[64:67], v[194:197], v[0:3], 0

; __device__ __forceinline__ float fsig(float x) { return __builtin_amdgcn_rcpf(1.0f + __expf(-x)); }
; template <bool PASS2>
; __device__ __forceinline__ void lru_item(const Frame& F, const Args& a, int item) {
;     ...
;             for (int e = 0; e < 16; ++e) { const int ee = dir ? 15 - e : e; const int rt = ee >> 2, j = ee & 3;
;                 const float rg = fsig(ar[rt][j] + ba), ig = fsig(ai[rt][j] + bi); const float la = logu * rg; const float av = __expf(la);
;                 const float mult = (t0 + tl0 + ee == tstart) ? 1.0f : __builtin_amdgcn_sqrtf(fmaxf(1.0f - av * av, 0.f)); const float bv = mult * ig * ax[rt][j];
;                 ar[rt][j] = av; ai[rt][j] = bv; B16 = av * B16 + bv; A16 = av * A16; }
.LBB0_182:
	v_fma_f32 v80, v80, s100, v181
	v_exp_f32_e32 v80, v80
	v_fma_f32 v76, v76, s100, v190
	v_add_f32_e32 v80, 1.0, v80
	v_rcp_f32_e32 v80, v80
	v_fma_f32 v81, v81, s100, v181
	v_exp_f32_e32 v76, v76
	v_exp_f32_e32 v81, v81
	v_mul_f32_e32 v80, v131, v80
	v_mul_f32_e32 v80, 0x3fb8aa3b, v80
	v_exp_f32_e32 v80, v80
	v_add_f32_e32 v76, 1.0, v76
	v_add_f32_e32 v81, 1.0, v81
	v_rcp_f32_e32 v76, v76
	v_fma_f32 v85, -v80, v80, 1.0
	v_max_f32_e32 v85, 0, v85
	v_sqrt_f32_e32 v85, v85
	v_add_u32_e32 v84, s39, v127
	v_rcp_f32_e32 v81, v81
	v_cmp_ne_u32_e32 vcc, 0, v84
	v_fma_f32 v82, v82, s100, v181
	v_cndmask_b32_e32 v84, 1.0, v85, vcc
	v_mul_f32_e32 v76, v76, v84
	v_mul_f32_e32 v64, v76, v64
	v_add_f32_e32 v76, v130, v77
	v_mul_f32_e32 v77, v131, v81
	v_mul_f32_e32 v77, 0x3fb8aa3b, v77
	v_mul_f32_e32 v76, 0xbfb8aa3b, v76
	v_exp_f32_e32 v77, v77
	v_exp_f32_e32 v76, v76
	v_exp_f32_e32 v82, v82
	v_fmac_f32_e32 v64, 0, v80
	v_fma_f32 v81, -v77, v77, 1.0
	v_add_f32_e32 v76, 1.0, v76
	v_max_f32_e32 v81, 0, v81
	v_rcp_f32_e32 v76, v76
	v_sqrt_f32_e32 v81, v81
	v_mul_f32_e32 v64, v77, v64
	v_mul_f32_e32 v77, v80, v77
	v_mul_f32_e32 v76, v76, v81
	v_fmac_f32_e32 v64, v76, v65
	v_add_f32_e32 v65, 1.0, v82
	v_rcp_f32_e32 v65, v65
	v_fma_f32 v76, v78, s100, v190
	v_exp_f32_e32 v76, v76
	v_mul_f32_e32 v65, v131, v65
	v_mul_f32_e32 v65, 0x3fb8aa3b, v65
	v_exp_f32_e32 v65, v65
	v_add_f32_e32 v76, 1.0, v76
	v_rcp_f32_e32 v76, v76
	v_fma_f32 v80, v83, s100, v181
	v_fma_f32 v78, -v65, v65, 1.0
	v_max_f32_e32 v78, 0, v78
	v_sqrt_f32_e32 v78, v78
	v_exp_f32_e32 v80, v80
	v_mul_f32_e32 v64, v65, v64
	v_mul_f32_e32 v65, v65, v77
	v_mul_f32_e32 v76, v76, v78
	v_fmac_f32_e32 v64, v76, v66
	v_add_f32_e32 v66, 1.0, v80
	v_rcp_f32_e32 v66, v66
	v_fma_f32 v76, v79, s100, v190
	v_exp_f32_e32 v76, v76
	v_mul_f32_e32 v66, v131, v66
	v_mul_f32_e32 v66, 0x3fb8aa3b, v66
	v_exp_f32_e32 v66, v66
	v_add_f32_e32 v76, 1.0, v76
	v_rcp_f32_e32 v76, v76
	v_fma_f32 v77, -v66, v66, 1.0
	v_max_f32_e32 v77, 0, v77
	v_sqrt_f32_e32 v77, v77
	v_fma_f32 v72, v72, s100, v181
	v_exp_f32_e32 v72, v72
	v_mul_f32_e32 v64, v66, v64
	v_mul_f32_e32 v76, v76, v77
	v_fmac_f32_e32 v64, v76, v67
	v_add_f32_e32 v67, 1.0, v72
	v_rcp_f32_e32 v67, v67
	v_fma_f32 v68, v68, s100, v190
	v_exp_f32_e32 v68, v68
	v_mul_f32_e32 v67, v131, v67
	v_mul_f32_e32 v67, 0x3fb8aa3b, v67
	v_exp_f32_e32 v67, v67
	v_mul_f32_e32 v65, v66, v65
	v_add_f32_e32 v66, 1.0, v68
	v_rcp_f32_e32 v66, v66
	v_fma_f32 v68, -v67, v67, 1.0
	v_max_f32_e32 v68, 0, v68
	v_sqrt_f32_e32 v68, v68
	v_fma_f32 v72, v73, s100, v181
	v_exp_f32_e32 v72, v72
	v_mul_f32_e32 v66, v66, v68
	v_mul_f32_e32 v52, v66, v52
	v_fmac_f32_e32 v52, v64, v67
	v_add_f32_e32 v64, 1.0, v72
	v_rcp_f32_e32 v64, v64
	v_fma_f32 v66, v69, s100, v190
	v_exp_f32_e32 v66, v66
	v_mul_f32_e32 v64, v131, v64
	v_mul_f32_e32 v64, 0x3fb8aa3b, v64
	v_exp_f32_e32 v64, v64
	v_mul_f32_e32 v65, v65, v67
	v_add_f32_e32 v66, 1.0, v66
	v_fma_f32 v67, -v64, v64, 1.0
	v_max_f32_e32 v67, 0, v67
	v_rcp_f32_e32 v66, v66
	v_sqrt_f32_e32 v67, v67
	v_fma_f32 v68, v74, s100, v181
	v_exp_f32_e32 v68, v68
	v_mul_f32_e32 v52, v64, v52
	v_mul_f32_e32 v66, v66, v67
	v_fmac_f32_e32 v52, v66, v53
	v_add_f32_e32 v53, 1.0, v68
	v_rcp_f32_e32 v53, v53
	v_fma_f32 v66, v70, s100, v190
	v_exp_f32_e32 v66, v66
	v_mul_f32_e32 v53, v131, v53
	v_mul_f32_e32 v53, 0x3fb8aa3b, v53
	v_exp_f32_e32 v53, v53
	v_mul_f32_e32 v64, v64, v65
	v_add_f32_e32 v65, 1.0, v66
	v_fma_f32 v66, -v53, v53, 1.0
	v_max_f32_e32 v66, 0, v66
	v_rcp_f32_e32 v65, v65
	v_sqrt_f32_e32 v66, v66
	v_fma_f32 v67, v75, s100, v181
	v_exp_f32_e32 v67, v67
	v_mul_f32_e32 v52, v53, v52
	v_mul_f32_e32 v65, v65, v66
	v_fmac_f32_e32 v52, v65, v54
	v_add_f32_e32 v54, 1.0, v67
	v_rcp_f32_e32 v54, v54
	v_fma_f32 v65, v71, s100, v190
	v_exp_f32_e32 v65, v65
	v_mul_f32_e32 v54, v131, v54
	v_mul_f32_e32 v54, 0x3fb8aa3b, v54
	v_exp_f32_e32 v54, v54
	v_mul_f32_e32 v53, v53, v64
	v_add_f32_e32 v64, 1.0, v65
	v_fma_f32 v65, -v54, v54, 1.0
	v_max_f32_e32 v65, 0, v65
	v_rcp_f32_e32 v64, v64
	v_sqrt_f32_e32 v65, v65
	v_fma_f32 v60, v60, s100, v181
	v_exp_f32_e32 v60, v60
	v_mul_f32_e32 v52, v54, v52
	v_mul_f32_e32 v64, v64, v65
	v_fmac_f32_e32 v52, v64, v55
	v_add_f32_e32 v55, 1.0, v60
	v_rcp_f32_e32 v55, v55
	v_fma_f32 v56, v56, s100, v190
	v_exp_f32_e32 v56, v56
	v_mul_f32_e32 v55, v131, v55
	v_mul_f32_e32 v55, 0x3fb8aa3b, v55
	v_exp_f32_e32 v55, v55
	v_mul_f32_e32 v53, v54, v53
	v_add_f32_e32 v54, 1.0, v56
	v_rcp_f32_e32 v54, v54
	v_fma_f32 v56, -v55, v55, 1.0
	v_max_f32_e32 v56, 0, v56
	v_sqrt_f32_e32 v56, v56
	v_fma_f32 v60, v61, s100, v181
	v_exp_f32_e32 v60, v60
	v_mul_f32_e32 v54, v54, v56
	v_mul_f32_e32 v40, v54, v40
; #define LAS __attribute__((address_space(3)))
; __device__ __forceinline__ unsigned cvt_pk_bf16(float lo, float hi) { unsigned r; asm volatile("v_cvt_pk_bf16_f32 %0, %1, %2" : "=v"(r) : "v"(lo), "v"(hi)); return r; }
; __device__ __forceinline__ float bf2f(unsigned short b) { return __uint_as_float(((unsigned)b) << 16); }
; __device__ __forceinline__ float fsig(float x) { return __builtin_amdgcn_rcpf(1.0f + __expf(-x)); }
; template <bool PASS2>
; __device__ __forceinline__ void lru_item(const Frame& F, const Args& a, int item) {
;     ...
;             for (int e = 0; e < 16; ++e) { const int ee = dir ? 15 - e : e; const int rt = ee >> 2, j = ee & 3;
;                 const float rg = fsig(ar[rt][j] + ba), ig = fsig(ai[rt][j] + bi); const float la = logu * rg; const float av = __expf(la);
;                 const float mult = (t0 + tl0 + ee == tstart) ? 1.0f : __builtin_amdgcn_sqrtf(fmaxf(1.0f - av * av, 0.f)); const float bv = mult * ig * ax[rt][j];
;                 ar[rt][j] = av; ai[rt][j] = bv; B16 = av * B16 + bv; A16 = av * A16; }
;             const int pos = dir ? 3 - fq : fq;
;             float PA = 1.f, PB = 0.f, QA = 1.f, QB = 0.f;
; #pragma unroll
;             for (int i = 0; i < 4; ++i) { const int k = dir ? 3 - i : i; const float Ak = __shfl(A16, fr + 16 * k), Bk = __shfl(B16, fr + 16 * k);
;                 if (i < pos) { PB = Ak * PB + Bk; PA = Ak * PA; }
;                 QB = Ak * QB + Bk; QA = Ak * QA; }
;             if (PASS2) {
;                 float h = PA * hc + PB;
; #pragma unroll
;                 for (int e = 0; e < 16; ++e) { const int ee = dir ? 15 - e : e; const int rt = ee >> 2, j = ee & 3; h = ar[rt][j] * h + ai[rt][j];
;                     if (dir == 0) hf[3][rt][j] = h;
;                     else { LAS unsigned short* yp = (LAS unsigned short*)(R0 + (tl0 + ee) * AT_PITCH + 2 * c); const float yb = bf2f(*yp);
;                         const float u2 = 1.5957691216057308f * (yb + 0.044715f * yb * yb * yb);
;                         const float y = (hf[3][rt][j] + h) * yb * fsig(u2);
;                         *yp = (unsigned short)(cvt_pk_bf16(y, 0.f) & 0xffffu); } }
;                 hc = QA * hc + QB;
;             } else { TB = QA * TB + QB; TA = QA * TA; }
	v_fmac_f32_e32 v40, v52, v55
	v_add_f32_e32 v52, 1.0, v60
	v_rcp_f32_e32 v52, v52
	v_fma_f32 v54, v57, s100, v190
	v_exp_f32_e32 v54, v54
	v_mul_f32_e32 v52, v131, v52
	v_mul_f32_e32 v52, 0x3fb8aa3b, v52
	v_exp_f32_e32 v52, v52
	v_mul_f32_e32 v53, v53, v55
	v_add_f32_e32 v54, 1.0, v54
	v_fma_f32 v55, -v52, v52, 1.0
	v_max_f32_e32 v55, 0, v55
	v_rcp_f32_e32 v54, v54
	v_sqrt_f32_e32 v55, v55
	v_fma_f32 v56, v62, s100, v181
	v_exp_f32_e32 v56, v56
	v_mul_f32_e32 v40, v52, v40
	v_mul_f32_e32 v54, v54, v55
	v_fmac_f32_e32 v40, v54, v41
	v_add_f32_e32 v41, 1.0, v56
	v_rcp_f32_e32 v41, v41
	v_fma_f32 v54, v58, s100, v190
	v_exp_f32_e32 v54, v54
	v_mul_f32_e32 v41, v131, v41
	v_mul_f32_e32 v41, 0x3fb8aa3b, v41
	v_exp_f32_e32 v41, v41
	v_mul_f32_e32 v52, v52, v53
	v_add_f32_e32 v53, 1.0, v54
	v_fma_f32 v54, -v41, v41, 1.0
	v_max_f32_e32 v54, 0, v54
	v_rcp_f32_e32 v53, v53
	v_sqrt_f32_e32 v54, v54
	v_fma_f32 v55, v63, s100, v181
	v_exp_f32_e32 v55, v55
	v_mul_f32_e32 v40, v41, v40
	v_mul_f32_e32 v53, v53, v54
	v_fmac_f32_e32 v40, v53, v42
	v_add_f32_e32 v42, 1.0, v55
	v_rcp_f32_e32 v42, v42
	v_fma_f32 v53, v59, s100, v190
	v_exp_f32_e32 v53, v53
	v_mul_f32_e32 v42, v131, v42
	v_mul_f32_e32 v42, 0x3fb8aa3b, v42
	v_exp_f32_e32 v54, v42
	v_mul_f32_e32 v41, v41, v52
	v_add_f32_e32 v42, 1.0, v53
	v_fma_f32 v52, -v54, v54, 1.0
	v_max_f32_e32 v52, 0, v52
	v_rcp_f32_e32 v42, v42
	v_sqrt_f32_e32 v52, v52
	v_fma_f32 v48, v48, s100, v181
	v_exp_f32_e32 v48, v48
	v_mul_f32_e32 v40, v54, v40
	v_mul_f32_e32 v42, v42, v52
	v_fmac_f32_e32 v40, v42, v43
	v_add_f32_e32 v42, 1.0, v48
	v_rcp_f32_e32 v42, v42
	v_fma_f32 v48, v49, s100, v181
	v_mul_f32_e32 v42, v131, v42
	v_fma_f32 v43, v44, s100, v190
	v_mul_f32_e32 v42, 0x3fb8aa3b, v42
	v_exp_f32_e32 v52, v48
	v_exp_f32_e32 v43, v43
	v_exp_f32_e32 v42, v42
	v_pk_mov_b32 v[48:49], v[36:37], v[36:37] op_sel:[1,0]
	v_add_f32_e32 v36, 1.0, v52
	v_mul_f32_e32 v44, v54, v41
	v_add_f32_e32 v41, 1.0, v43
	v_fma_f32 v43, -v42, v42, 1.0
	v_rcp_f32_e32 v36, v36
	v_max_f32_e32 v43, 0, v43
	v_rcp_f32_e32 v41, v41
	v_sqrt_f32_e32 v43, v43
	v_fma_f32 v50, v50, s100, v181
	v_exp_f32_e32 v50, v50
	v_mul_f32_e32 v36, v131, v36
	v_mul_f32_e32 v36, 0x3fb8aa3b, v36
	v_mul_f32_e32 v41, v41, v43
	v_mov_b32_e32 v43, v49
	v_fma_f32 v45, v45, s100, v190
	v_exp_f32_e32 v49, v36
	v_mul_f32_e32 v36, v40, v42
	v_exp_f32_e32 v45, v45
	v_pk_fma_f32 v[40:41], v[40:41], v[42:43], v[36:37] op_sel_hi:[1,1,0]
	v_add_f32_e32 v36, 1.0, v50
	v_rcp_f32_e32 v36, v36
	v_fma_f32 v52, -v49, v49, 1.0
	v_add_f32_e32 v45, 1.0, v45
	v_max_f32_e32 v52, 0, v52
	v_rcp_f32_e32 v45, v45
	v_sqrt_f32_e32 v52, v52
	v_fma_f32 v43, v46, s100, v190
	v_mul_f32_e32 v36, v131, v36
	v_mul_f32_e32 v42, v44, v42
	v_exp_f32_e32 v44, v43
	v_mul_f32_e32 v36, 0x3fb8aa3b, v36
	v_exp_f32_e32 v43, v36
	v_mul_f32_e32 v40, v45, v52
	v_mul_f32_e32 v36, v40, v37
	v_add_f32_e32 v37, 1.0, v44
	v_rcp_f32_e32 v44, v37
	v_fma_f32 v37, -v43, v43, 1.0
	v_max_f32_e32 v37, 0, v37
	v_sqrt_f32_e32 v45, v37
	v_fma_f32 v37, v51, s100, v181
	v_exp_f32_e32 v46, v37
	v_pk_fma_f32 v[36:37], v[40:41], v[48:49], v[36:37] op_sel_hi:[1,1,0]
	v_mul_f32_e32 v40, v49, v42
	v_add_f32_e32 v41, 1.0, v46
	v_rcp_f32_e32 v41, v41
	v_fma_f32 v42, v47, s100, v190
	v_mul_f32_e32 v36, v44, v45
	v_exp_f32_e32 v44, v42
	v_mul_f32_e32 v41, v131, v41
	v_mul_f32_e32 v41, 0x3fb8aa3b, v41
	v_exp_f32_e32 v41, v41
	v_add_f32_e32 v44, 1.0, v44
	v_rcp_f32_e32 v44, v44
	v_mov_b32_e32 v42, v38
	v_fma_f32 v45, -v41, v41, 1.0
	v_max_f32_e32 v45, 0, v45
	v_sqrt_f32_e32 v45, v45
	v_mul_f32_e32 v38, v36, v38
	v_pk_fma_f32 v[36:37], v[36:37], v[42:43], v[38:39] op_sel_hi:[1,1,0]
	v_mul_f32_e32 v42, v43, v40
	v_mul_f32_e32 v36, v44, v45
	v_mov_b32_e32 v40, v39
	v_mul_f32_e32 v38, v37, v41
	v_pk_fma_f32 v[36:37], v[36:37], v[40:41], v[38:39] op_sel_hi:[1,1,0]
	ds_bpermute_b32 v43, v124, v36
	v_mul_f32_e32 v37, v41, v42
	ds_bpermute_b32 v40, v122, v37
	ds_bpermute_b32 v41, v122, v36
	ds_bpermute_b32 v42, v124, v37
	ds_bpermute_b32 v38, v125, v37
	ds_bpermute_b32 v44, v125, v36
	ds_bpermute_b32 v39, v126, v37
	s_waitcnt lgkmcnt(4)
	v_fmac_f32_e32 v41, 0, v40
	ds_bpermute_b32 v45, v126, v36
	s_waitcnt lgkmcnt(4)
	v_fmac_f32_e32 v43, v41, v42
	s_waitcnt lgkmcnt(3)
	v_mul_f32_e32 v37, v43, v38
	v_mul_f32_e32 v36, v40, v42
	s_waitcnt lgkmcnt(2)
	v_add_f32_e32 v37, v37, v44
	s_waitcnt lgkmcnt(1)
	v_pk_mul_f32 v[36:37], v[36:37], v[38:39]
	s_add_i32 s39, s39, 64
	v_mul_f32_e32 v36, v36, v39
	s_waitcnt lgkmcnt(0)
	v_add_f32_e32 v107, v37, v45
	v_fmac_f32_e32 v107, v129, v36
	v_mul_f32_e32 v106, v106, v36
	s_cmpk_eq_i32 s39, 0x100
	v_add_u32_e32 v132, 0x4400, v132
	s_cbranch_scc1 .LBB0_184
	v_mov_b32_e32 v129, v107
	s_branch .LBB0_150

; #define LAS __attribute__((address_space(3)))
; __device__ __forceinline__ float fsig(float x) { return __builtin_amdgcn_rcpf(1.0f + __expf(-x)); }
; template <bool PASS2>
; __device__ __forceinline__ void lru_item(const Frame& F, const Args& a, int item) {
;     ...
;                 for (int ks = 0; ks < 4; ++ks) { const bf16x8 xf = *(const LAS bf16x8*)(AT + (64 * s + 16 * rt + fr) * AT_PITCH + 64 * ks + 16 * fq);
;                     ar[rt] = __builtin_amdgcn_mfma_f32_16x16x32_bf16(xf, wrf[ks], ar[rt], 0, 0, 0); ai[rt] = __builtin_amdgcn_mfma_f32_16x16x32_bf16(xf, wif[ks], ai[rt], 0, 0, 0);
;                     if (ks == ks0) ax[rt] = __builtin_amdgcn_mfma_f32_16x16x32_bf16(xf, sel, ax[rt], 0, 0, 0); } }
;             const int tl0 = 64 * s + 16 * fq;
;             float A16 = 1.f, B16 = 0.f;
; #pragma unroll
;             for (int e = 0; e < 16; ++e) { const int ee = dir ? 15 - e : e; const int rt = ee >> 2, j = ee & 3;
;                 const float rg = fsig(ar[rt][j] + ba), ig = fsig(ai[rt][j] + bi); const float la = logu * rg; const float av = __expf(la);
.LBB0_187:
	s_mov_b32 s100, 0xbfb8aa3b
	v_mul_f32_e32 v181, 0xbfb8aa3b, v128
	v_mul_f32_e32 v190, 0xbfb8aa3b, v129
	v_bitop3_b32 v36, s39, v101, v123 bitop3:0xde
	v_mul_lo_u32 v36, v36, s45
	v_add_u32_e32 v107, v110, v36
	ds_read_b128 v[194:197], v107
	ds_read_b128 v[198:201], v107 offset:64
	ds_read_b128 v[202:205], v107 offset:128
	ds_read_b128 v[206:209], v107 offset:192
	ds_read_b128 v[210:213], v107 offset:4352
	ds_read_b128 v[214:217], v107 offset:4416
	ds_read_b128 v[218:221], v107 offset:4480
	ds_read_b128 v[222:225], v107 offset:4544
	ds_read_b128 v[226:229], v107 offset:8704
	ds_read_b128 v[248:251], v107 offset:8768
	ds_read_b128 v[252:255], v107 offset:8832
	s_mov_b32 s14, s12
	s_mov_b32 s15, s12
	s_mov_b32 s13, s12
	v_mov_b64_e32 v[38:39], s[14:15]
	s_and_b64 vcc, exec, s[10:11]
	v_mov_b64_e32 v[36:37], s[12:13]
	s_waitcnt vmcnt(9) lgkmcnt(10)
	v_mfma_f32_16x16x32_bf16 v[44:47], v[194:197], v[4:7], 0
	s_waitcnt vmcnt(3)
	v_mfma_f32_16x16x32_bf16 v[48:51], v[194:197], v[20:23], 0
	s_cbranch_vccnz .LBB0_189
	v_mfma_f32_16x16x32_bf16 v[36:39], v[194:197], v[0:3], 0

; __device__ __forceinline__ float fsig(float x) { return __builtin_amdgcn_rcpf(1.0f + __expf(-x)); }
; template <bool PASS2>
; __device__ __forceinline__ void lru_item(const Frame& F, const Args& a, int item) {
;     ...
;             for (int e = 0; e < 16; ++e) { const int ee = dir ? 15 - e : e; const int rt = ee >> 2, j = ee & 3;
;                 const float rg = fsig(ar[rt][j] + ba), ig = fsig(ai[rt][j] + bi); const float la = logu * rg; const float av = __expf(la);
;                 const float mult = (t0 + tl0 + ee == tstart) ? 1.0f : __builtin_amdgcn_sqrtf(fmaxf(1.0f - av * av, 0.f)); const float bv = mult * ig * ax[rt][j];
;                 ar[rt][j] = av; ai[rt][j] = bv; B16 = av * B16 + bv; A16 = av * A16; }
.LBB0_219:
	s_nop 4
	v_fma_f32 v83, v83, s100, v181
	v_exp_f32_e32 v83, v83
	v_fma_f32 v82, v82, s100, v181
	v_exp_f32_e32 v82, v82
	v_add_f32_e32 v83, 1.0, v83
	v_rcp_f32_e32 v83, v83
	v_fma_f32 v79, v79, s100, v190
	v_add_f32_e32 v82, 1.0, v82
	v_mul_f32_e32 v83, v130, v83
	v_mul_f32_e32 v83, 0x3fb8aa3b, v83
	v_exp_f32_e32 v83, v83
	v_exp_f32_e32 v79, v79
	v_rcp_f32_e32 v82, v82
	s_xor_b32 s13, s39, 0xc0
	v_fma_f32 v85, -v83, v83, 1.0
	v_max_f32_e32 v85, 0, v85
	v_add_f32_e32 v79, 1.0, v79
	v_sqrt_f32_e32 v85, v85
	v_mul_f32_e32 v82, v130, v82
	v_rcp_f32_e32 v79, v79
	v_mul_f32_e32 v82, 0x3fb8aa3b, v82
	v_add_u32_e32 v84, s13, v127
	v_fma_f32 v78, v78, s100, v190
	v_exp_f32_e32 v82, v82
	v_cmp_ne_u32_e32 vcc, s54, v84
	v_exp_f32_e32 v78, v78
	v_cndmask_b32_e32 v84, 1.0, v85, vcc
	v_mul_f32_e32 v79, v79, v84
	v_mul_f32_e32 v75, v79, v75
	v_fma_f32 v79, -v82, v82, 1.0
	v_add_f32_e32 v78, 1.0, v78
	v_max_f32_e32 v79, 0, v79
	v_fma_f32 v81, v81, s100, v181
	v_rcp_f32_e32 v78, v78
	v_sqrt_f32_e32 v79, v79
	v_exp_f32_e32 v81, v81
	v_fma_f32 v77, v77, s100, v190
	v_mul_f32_e32 v78, v78, v79
	v_add_f32_e32 v79, 1.0, v81
	v_rcp_f32_e32 v79, v79
	v_exp_f32_e32 v77, v77
	v_fmac_f32_e32 v75, 0, v83
	v_mul_f32_e32 v75, v82, v75
	v_mul_f32_e32 v79, v130, v79
	v_mul_f32_e32 v79, 0x3fb8aa3b, v79
	v_exp_f32_e32 v79, v79
	v_fmac_f32_e32 v75, v78, v74
	v_add_f32_e32 v74, 1.0, v77
	v_fma_f32 v77, -v79, v79, 1.0
	v_max_f32_e32 v77, 0, v77
	v_fma_f32 v78, v80, s100, v181
	v_rcp_f32_e32 v74, v74
	v_sqrt_f32_e32 v77, v77
	v_exp_f32_e32 v78, v78
	v_fma_f32 v71, v71, s100, v181
	v_mul_f32_e32 v74, v74, v77
	v_add_f32_e32 v77, 1.0, v78
	v_rcp_f32_e32 v77, v77
	v_exp_f32_e32 v71, v71
	v_fma_f32 v76, v76, s100, v190
	v_mul_f32_e32 v77, v130, v77
	v_mul_f32_e32 v77, 0x3fb8aa3b, v77
	v_exp_f32_e32 v77, v77
	v_add_f32_e32 v71, 1.0, v71
	v_exp_f32_e32 v76, v76
	v_rcp_f32_e32 v71, v71
	v_fma_f32 v70, v70, s100, v181
	v_mul_f32_e32 v75, v79, v75
	v_exp_f32_e32 v70, v70
	v_fmac_f32_e32 v75, v74, v73
	v_fma_f32 v74, -v77, v77, 1.0
	v_add_f32_e32 v73, 1.0, v76
	v_max_f32_e32 v74, 0, v74
	v_mul_f32_e32 v71, v130, v71
	v_rcp_f32_e32 v73, v73
	v_sqrt_f32_e32 v74, v74
	v_mul_f32_e32 v71, 0x3fb8aa3b, v71
	v_fma_f32 v67, v67, s100, v190
	v_exp_f32_e32 v71, v71
	v_add_f32_e32 v70, 1.0, v70
	v_exp_f32_e32 v67, v67
	v_rcp_f32_e32 v70, v70
	v_mul_f32_e32 v73, v73, v74
	v_mul_f32_e32 v74, v77, v75
	v_fmac_f32_e32 v74, v73, v72
	v_fma_f32 v72, -v71, v71, 1.0
	v_add_f32_e32 v67, 1.0, v67
	v_max_f32_e32 v72, 0, v72
	v_mul_f32_e32 v70, v130, v70
	v_rcp_f32_e32 v67, v67
	v_sqrt_f32_e32 v72, v72
	v_fma_f32 v66, v66, s100, v190
	v_mul_f32_e32 v70, 0x3fb8aa3b, v70
	v_exp_f32_e32 v66, v66
	v_exp_f32_e32 v70, v70
	v_mul_f32_e32 v67, v67, v72
	v_mul_f32_e32 v72, v71, v74
	v_fmac_f32_e32 v72, v67, v63
	v_add_f32_e32 v63, 1.0, v66
	v_fma_f32 v66, -v70, v70, 1.0
	v_max_f32_e32 v66, 0, v66
	v_fma_f32 v67, v69, s100, v181
	v_rcp_f32_e32 v63, v63
	v_sqrt_f32_e32 v66, v66
	v_exp_f32_e32 v67, v67
	v_fma_f32 v65, v65, s100, v190
	v_exp_f32_e32 v65, v65
	v_mul_f32_e32 v63, v63, v66
	v_mul_f32_e32 v66, v70, v72
	v_add_f32_e32 v67, 1.0, v67
	v_rcp_f32_e32 v67, v67
	v_fmac_f32_e32 v66, v63, v62
	v_add_f32_e32 v62, 1.0, v65
	v_fma_f32 v65, v68, s100, v181
	v_exp_f32_e32 v65, v65
	v_mul_f32_e32 v67, v130, v67
	v_mul_f32_e32 v67, 0x3fb8aa3b, v67
	v_exp_f32_e32 v67, v67
	v_add_f32_e32 v65, 1.0, v65
	v_rcp_f32_e32 v65, v65
	v_fma_f32 v59, v59, s100, v181
	v_exp_f32_e32 v59, v59
	v_fma_f32 v63, -v67, v67, 1.0
	v_max_f32_e32 v63, 0, v63
	v_mul_f32_e32 v65, v130, v65
	v_rcp_f32_e32 v62, v62
	v_sqrt_f32_e32 v63, v63
	v_mul_f32_e32 v65, 0x3fb8aa3b, v65
	v_fma_f32 v64, v64, s100, v190
	v_exp_f32_e32 v65, v65
	v_add_f32_e32 v59, 1.0, v59
	v_exp_f32_e32 v64, v64
	v_rcp_f32_e32 v59, v59
	v_fma_f32 v58, v58, s100, v181
	v_mul_f32_e32 v62, v62, v63
	v_mul_f32_e32 v63, v67, v66
	v_exp_f32_e32 v58, v58
	v_fmac_f32_e32 v63, v62, v61
	v_fma_f32 v62, -v65, v65, 1.0
	v_add_f32_e32 v61, 1.0, v64
	v_max_f32_e32 v62, 0, v62
	v_mul_f32_e32 v59, v130, v59
	v_rcp_f32_e32 v61, v61
	v_sqrt_f32_e32 v62, v62
	v_mul_f32_e32 v59, 0x3fb8aa3b, v59
	v_fma_f32 v55, v55, s100, v190
	v_exp_f32_e32 v59, v59
	v_add_f32_e32 v58, 1.0, v58
	v_exp_f32_e32 v55, v55
	v_rcp_f32_e32 v58, v58
	v_mul_f32_e32 v61, v61, v62
	v_mul_f32_e32 v62, v65, v63
	v_fmac_f32_e32 v62, v61, v60
	v_fma_f32 v60, -v59, v59, 1.0
	v_add_f32_e32 v55, 1.0, v55
	v_max_f32_e32 v60, 0, v60
	v_mul_f32_e32 v58, v130, v58
	v_rcp_f32_e32 v55, v55
	v_sqrt_f32_e32 v60, v60
	v_fma_f32 v54, v54, s100, v190
	v_mul_f32_e32 v58, 0x3fb8aa3b, v58
	v_exp_f32_e32 v54, v54
	v_exp_f32_e32 v58, v58
	v_mul_f32_e32 v55, v55, v60
; #define LAS __attribute__((address_space(3)))
; __device__ __forceinline__ unsigned cvt_pk_bf16(float lo, float hi) { unsigned r; asm volatile("v_cvt_pk_bf16_f32 %0, %1, %2" : "=v"(r) : "v"(lo), "v"(hi)); return r; }
; __device__ __forceinline__ float bf2f(unsigned short b) { return __uint_as_float(((unsigned)b) << 16); }
; __device__ __forceinline__ float fsig(float x) { return __builtin_amdgcn_rcpf(1.0f + __expf(-x)); }
; template <bool PASS2>
; __device__ __forceinline__ void lru_item(const Frame& F, const Args& a, int item) {
;     ...
;             for (int e = 0; e < 16; ++e) { const int ee = dir ? 15 - e : e; const int rt = ee >> 2, j = ee & 3;
;                 const float rg = fsig(ar[rt][j] + ba), ig = fsig(ai[rt][j] + bi); const float la = logu * rg; const float av = __expf(la);
;                 const float mult = (t0 + tl0 + ee == tstart) ? 1.0f : __builtin_amdgcn_sqrtf(fmaxf(1.0f - av * av, 0.f)); const float bv = mult * ig * ax[rt][j];
;                 ar[rt][j] = av; ai[rt][j] = bv; B16 = av * B16 + bv; A16 = av * A16; }
;             const int pos = dir ? 3 - fq : fq;
;             float PA = 1.f, PB = 0.f, QA = 1.f, QB = 0.f;
; #pragma unroll
;             for (int i = 0; i < 4; ++i) { const int k = dir ? 3 - i : i; const float Ak = __shfl(A16, fr + 16 * k), Bk = __shfl(B16, fr + 16 * k);
;                 if (i < pos) { PB = Ak * PB + Bk; PA = Ak * PA; }
;                 QB = Ak * QB + Bk; QA = Ak * QA; }
;             if (PASS2) {
;                 float h = PA * hc + PB;
; #pragma unroll
;                 for (int e = 0; e < 16; ++e) { const int ee = dir ? 15 - e : e; const int rt = ee >> 2, j = ee & 3; h = ar[rt][j] * h + ai[rt][j];
;                     if (dir == 0) hf[3][rt][j] = h;
;                     else { LAS unsigned short* yp = (LAS unsigned short*)(R0 + (tl0 + ee) * AT_PITCH + 2 * c); const float yb = bf2f(*yp);
;                         const float u2 = 1.5957691216057308f * (yb + 0.044715f * yb * yb * yb);
;                         const float y = (hf[3][rt][j] + h) * yb * fsig(u2);
;                         *yp = (unsigned short)(cvt_pk_bf16(y, 0.f) & 0xffffu); } }
;                 hc = QA * hc + QB;
;             } else { TB = QA * TB + QB; TA = QA * TA; }
	v_mul_f32_e32 v60, v59, v62
	v_fmac_f32_e32 v60, v55, v51
	v_add_f32_e32 v51, 1.0, v54
	v_fma_f32 v54, -v58, v58, 1.0
	v_max_f32_e32 v54, 0, v54
	v_fma_f32 v55, v57, s100, v181
	v_rcp_f32_e32 v51, v51
	v_sqrt_f32_e32 v54, v54
	v_exp_f32_e32 v55, v55
	v_fma_f32 v53, v53, s100, v190
	v_exp_f32_e32 v53, v53
	v_mul_f32_e32 v51, v51, v54
	v_mul_f32_e32 v54, v58, v60
	v_add_f32_e32 v55, 1.0, v55
	v_rcp_f32_e32 v55, v55
	v_fmac_f32_e32 v54, v51, v50
	v_add_f32_e32 v50, 1.0, v53
	v_fma_f32 v53, v56, s100, v181
	v_exp_f32_e32 v53, v53
	v_mul_f32_e32 v55, v130, v55
	v_mul_f32_e32 v55, 0x3fb8aa3b, v55
	v_exp_f32_e32 v55, v55
	v_add_f32_e32 v53, 1.0, v53
	v_rcp_f32_e32 v53, v53
	v_rcp_f32_e32 v50, v50
	v_fma_f32 v51, -v55, v55, 1.0
	v_max_f32_e32 v51, 0, v51
	v_mul_f32_e32 v53, v130, v53
	v_sqrt_f32_e32 v51, v51
	v_mul_f32_e32 v53, 0x3fb8aa3b, v53
	v_fma_f32 v52, v52, s100, v190
	v_exp_f32_e32 v53, v53
	v_exp_f32_e32 v52, v52
	v_mul_f32_e32 v50, v50, v51
	v_mul_f32_e32 v51, v55, v54
	v_fmac_f32_e32 v51, v50, v49
	v_fma_f32 v50, -v53, v53, 1.0
	v_add_f32_e32 v49, 1.0, v52
	v_max_f32_e32 v50, 0, v50
	v_fma_f32 v47, v47, s100, v181
	v_rcp_f32_e32 v49, v49
	v_sqrt_f32_e32 v50, v50
	v_exp_f32_e32 v52, v47
	v_fma_f32 v43, v43, s100, v190
	v_mul_f32_e32 v50, v49, v50
	v_add_f32_e32 v49, 1.0, v52
	v_rcp_f32_e32 v49, v49
	v_exp_f32_e32 v43, v43
	v_mul_f32_e32 v47, v53, v51
	v_fmac_f32_e32 v47, v50, v48
	v_mul_f32_e32 v49, v130, v49
	v_mul_f32_e32 v49, 0x3fb8aa3b, v49
	v_exp_f32_e32 v49, v49
	v_add_f32_e32 v43, 1.0, v43
	v_rcp_f32_e32 v43, v43
	v_fma_f32 v48, -v49, v49, 1.0
	v_max_f32_e32 v48, 0, v48
	v_sqrt_f32_e32 v48, v48
	v_fma_f32 v46, v46, s100, v181
	v_exp_f32_e32 v51, v46
	v_mul_f32_e32 v80, v83, v82
	v_mul_f32_e32 v46, v43, v48
	v_mov_b32_e32 v48, v39
	v_mul_f32_e32 v50, v46, v39
	v_add_f32_e32 v39, 1.0, v51
	v_rcp_f32_e32 v39, v39
	v_mul_f32_e32 v76, v79, v80
	v_mul_f32_e32 v73, v77, v76
	v_fma_f32 v42, v42, s100, v190
	v_mul_f32_e32 v39, v130, v39
	v_mul_f32_e32 v69, v71, v73
	v_exp_f32_e32 v42, v42
	v_mul_f32_e32 v39, 0x3fb8aa3b, v39
	v_mul_f32_e32 v68, v70, v69
	v_exp_f32_e32 v39, v39
	v_mul_f32_e32 v64, v67, v68
	v_mul_f32_e32 v61, v65, v64
	v_mul_f32_e32 v57, v59, v61
	v_add_f32_e32 v42, 1.0, v42
	v_mul_f32_e32 v56, v58, v57
	v_rcp_f32_e32 v52, v42
	v_fma_f32 v42, -v39, v39, 1.0
	v_mul_f32_e32 v54, v55, v56
	v_max_f32_e32 v42, 0, v42
	v_mul_f32_e32 v51, v53, v54
	v_sqrt_f32_e32 v53, v42
	v_fma_f32 v42, v45, s100, v181
	v_exp_f32_e32 v45, v42
	v_fma_f32 v41, v41, s100, v190
	v_exp_f32_e32 v41, v41
	v_add_f32_e32 v45, 1.0, v45
	v_rcp_f32_e32 v45, v45
	v_pk_fma_f32 v[42:43], v[46:47], v[48:49], v[50:51] op_sel_hi:[1,1,0]
	v_mul_f32_e32 v42, v52, v53
	v_mul_f32_e32 v45, v130, v45
	v_mul_f32_e32 v45, 0x3fb8aa3b, v45
	v_exp_f32_e32 v45, v45
	v_mul_f32_e32 v46, v42, v38
	v_pk_fma_f32 v[42:43], v[42:43], v[38:39], v[46:47] op_sel_hi:[1,1,0]
	v_add_f32_e32 v38, 1.0, v41
	v_fma_f32 v41, -v45, v45, 1.0
	v_max_f32_e32 v41, 0, v41
	v_rcp_f32_e32 v38, v38
	v_sqrt_f32_e32 v41, v41
	v_fma_f32 v42, v44, s100, v181
	v_exp_f32_e32 v46, v42
	v_mov_b32_e32 v44, v37
	v_mul_f32_e32 v42, v38, v41
	v_mul_f32_e32 v38, v42, v37
	v_add_f32_e32 v37, 1.0, v46
	v_rcp_f32_e32 v37, v37
	v_fma_f32 v40, v40, s100, v190
	v_exp_f32_e32 v40, v40
	v_mul_f32_e32 v41, v49, v51
	v_mul_f32_e32 v37, v130, v37
	v_mul_f32_e32 v37, 0x3fb8aa3b, v37
	v_exp_f32_e32 v37, v37
	v_add_f32_e32 v40, 1.0, v40
	v_rcp_f32_e32 v40, v40
	v_mul_f32_e32 v41, v39, v41
	v_fma_f32 v46, -v37, v37, 1.0
	v_max_f32_e32 v46, 0, v46
	v_sqrt_f32_e32 v46, v46
	v_pk_fma_f32 v[38:39], v[42:43], v[44:45], v[38:39] op_sel_hi:[1,1,0]
	v_mul_f32_e32 v41, v45, v41
	s_add_i32 s39, s39, 64
	v_mul_f32_e32 v38, v40, v46
	v_mul_f32_e32 v40, v39, v37
	v_pk_fma_f32 v[38:39], v[38:39], v[36:37], v[40:41] op_sel_hi:[1,1,0]
	v_mul_f32_e32 v37, v37, v41
	ds_bpermute_b32 v39, v126, v37
	ds_bpermute_b32 v40, v126, v38
	ds_bpermute_b32 v41, v125, v37
	ds_bpermute_b32 v42, v125, v38
	ds_bpermute_b32 v36, v124, v37
	ds_bpermute_b32 v43, v124, v38
	ds_bpermute_b32 v37, v122, v37
	s_waitcnt lgkmcnt(5)
	v_fmac_f32_e32 v40, 0, v39
	ds_bpermute_b32 v44, v122, v38
	s_waitcnt lgkmcnt(4)
	v_fmac_f32_e32 v42, v40, v41
	s_waitcnt lgkmcnt(3)
	v_mul_f32_e32 v40, v42, v36
	v_mul_f32_e32 v38, v39, v41
	s_waitcnt lgkmcnt(2)
	v_add_f32_e32 v39, v40, v43
	s_waitcnt lgkmcnt(1)
	v_pk_mul_f32 v[38:39], v[38:39], v[36:37]
	s_cmpk_eq_i32 s39, 0x100
	v_mul_f32_e32 v36, v38, v37
	s_waitcnt lgkmcnt(0)
	v_add_f32_e32 v107, v39, v44
	v_fmac_f32_e32 v107, v131, v36
	v_mul_f32_e32 v106, v106, v36
	s_cbranch_scc1 .LBB0_221
	v_mov_b32_e32 v131, v107
	s_branch .LBB0_187

; #define LAS __attribute__((address_space(3)))
; __device__ __forceinline__ float fsig(float x) { return __builtin_amdgcn_rcpf(1.0f + __expf(-x)); }
; template <bool PASS2>
; __device__ __forceinline__ void lru_item(const Frame& F, const Args& a, int item) {
;     ...
;             if (PASS2 && dir == 0) {
; #pragma unroll
;                 for (int i1 = 0; i1 < 4; ++i1)
; #pragma unroll
;                     for (int i2 = 0; i2 < 4; ++i2) { hf[0][i1][i2] = hf[1][i1][i2]; hf[1][i1][i2] = hf[2][i1][i2]; hf[2][i1][i2] = hf[3][i1][i2]; } }
;             f32x4 ar[4], ai[4], ax[4];
; #pragma unroll
;             for (int rt = 0; rt < 4; ++rt) { ar[rt] = (f32x4){0.f, 0.f, 0.f, 0.f}; ai[rt] = (f32x4){0.f, 0.f, 0.f, 0.f}; ax[rt] = (f32x4){0.f, 0.f, 0.f, 0.f};
; #pragma unroll
;                 for (int ks = 0; ks < 4; ++ks) { const bf16x8 xf = *(const LAS bf16x8*)(AT + (64 * s + 16 * rt + fr) * AT_PITCH + 64 * ks + 16 * fq);
;                     ar[rt] = __builtin_amdgcn_mfma_f32_16x16x32_bf16(xf, wrf[ks], ar[rt], 0, 0, 0); ai[rt] = __builtin_amdgcn_mfma_f32_16x16x32_bf16(xf, wif[ks], ai[rt], 0, 0, 0);
;                     if (ks == ks0) ax[rt] = __builtin_amdgcn_mfma_f32_16x16x32_bf16(xf, sel, ax[rt], 0, 0, 0); } }
;             const int tl0 = 64 * s + 16 * fq;
;             float A16 = 1.f, B16 = 0.f;
; #pragma unroll
;             for (int e = 0; e < 16; ++e) { const int ee = dir ? 15 - e : e; const int rt = ee >> 2, j = ee & 3;
;                 const float rg = fsig(ar[rt][j] + ba), ig = fsig(ai[rt][j] + bi); const float la = logu * rg; const float av = __expf(la);
.LBB0_708:
	s_mov_b32 s100, 0xbfb8aa3b
	v_mul_f32_e32 v211, 0xbfb8aa3b, v204
	v_mul_f32_e32 v241, 0xbfb8aa3b, v206
	v_add_u32_e32 v125, v209, v105
	v_add_u32_e32 v240, 0x11400, v125
	ds_read_b128 v[212:215], v240
	ds_read_b128 v[216:219], v240 offset:64
	ds_read_b128 v[220:223], v240 offset:128
	ds_read_b128 v[224:227], v240 offset:192
	ds_read_b128 v[228:231], v240 offset:4352
	ds_read_b128 v[232:235], v240 offset:4416
	ds_read_b128 v[236:239], v240 offset:4480
	ds_read_b128 v[244:247], v240 offset:4544
	ds_read_b128 v[248:251], v240 offset:8704
	ds_read_b128 v[252:255], v240 offset:8768
	v_mov_b32_e32 v182, v4
	v_mov_b32_e32 v179, v7
	v_mov_b32_e32 v180, v6
	v_mov_b32_e32 v181, v5
	v_mov_b32_e32 v174, v12
	v_cndmask_b32_e64 v12, 0, 1, s[36:37]
	v_mov_b32_e32 v173, v13
	v_mov_b32_e32 v175, v11
	v_mov_b32_e32 v176, v10
	v_mov_b32_e32 v177, v9
	v_mov_b32_e32 v178, v8
	s_waitcnt lgkmcnt(9)
	v_mfma_f32_16x16x32_bf16 v[8:11], v[212:215], v[36:39], 0
	v_cmp_ne_u32_e64 s[8:9], 1, v12
	s_mov_b32 s29, s28
	s_mov_b32 s30, s28
	v_mfma_f32_16x16x32_bf16 v[12:15], v[212:215], v[44:47], 0
	s_mov_b32 s31, s28
	v_mov_b64_e32 v[28:29], s[28:29]
	v_mov_b32_e32 v183, v132
	v_mov_b32_e32 v184, v131
	v_mov_b32_e32 v185, v146
	v_mov_b32_e32 v186, v145
	v_mov_b32_e32 v187, v143
	v_mov_b32_e32 v188, v133
	v_mov_b32_e32 v132, v198
	v_mov_b32_e32 v131, v200
	v_mov_b32_e32 v146, v202
	v_mov_b32_e32 v145, v203
	v_mov_b32_e32 v143, v205
	v_mov_b32_e32 v133, v124
	v_mov_b64_e32 v[30:31], s[30:31]
	s_andn2_b64 vcc, exec, s[36:37]
	s_cbranch_vccnz .LBB0_710
	v_mfma_f32_16x16x32_bf16 v[28:31], v[212:215], v[0:3], 0

; __device__ __forceinline__ float fsig(float x) { return __builtin_amdgcn_rcpf(1.0f + __expf(-x)); }
; template <bool PASS2>
; __device__ __forceinline__ void lru_item(const Frame& F, const Args& a, int item) {
;     ...
;             for (int e = 0; e < 16; ++e) { const int ee = dir ? 15 - e : e; const int rt = ee >> 2, j = ee & 3;
;                 const float rg = fsig(ar[rt][j] + ba), ig = fsig(ai[rt][j] + bi); const float la = logu * rg; const float av = __expf(la);
;                 const float mult = (t0 + tl0 + ee == tstart) ? 1.0f : __builtin_amdgcn_sqrtf(fmaxf(1.0f - av * av, 0.f)); const float bv = mult * ig * ax[rt][j];
;                 ar[rt][j] = av; ai[rt][j] = bv; B16 = av * B16 + bv; A16 = av * A16; }
.LBB0_740:
	v_fma_f32 v80, v80, s100, v211
	v_exp_f32_e32 v80, v80
	v_fma_f32 v81, v81, s100, v211
	v_exp_f32_e32 v81, v81
	v_add_f32_e32 v80, 1.0, v80
	v_rcp_f32_e32 v80, v80
	v_add_f32_e32 v81, 1.0, v81
	v_rcp_f32_e32 v81, v81
	v_mul_f32_e32 v80, v207, v80
	v_mul_f32_e32 v80, 0x3fb8aa3b, v80
	v_exp_f32_e32 v80, v80
	v_mul_f32_e32 v81, v207, v81
	v_fma_f32 v76, v76, s100, v241
	v_fma_f32 v85, -v80, v80, 1.0
	v_max_f32_e32 v85, 0, v85
	v_mul_f32_e32 v81, 0x3fb8aa3b, v81
	v_exp_f32_e32 v76, v76
	v_sqrt_f32_e32 v85, v85
	v_fma_f32 v77, v77, s100, v241
	v_exp_f32_e32 v81, v81
	v_exp_f32_e32 v77, v77
	v_add_u32_e32 v84, s49, v208
	v_cmp_ne_u32_e32 vcc, 0, v84
	v_add_f32_e32 v76, 1.0, v76
	v_rcp_f32_e32 v76, v76
	v_cndmask_b32_e32 v84, 1.0, v85, vcc
	v_fma_f32 v85, -v81, v81, 1.0
	v_add_f32_e32 v77, 1.0, v77
	v_max_f32_e32 v85, 0, v85
	v_rcp_f32_e32 v77, v77
	v_sqrt_f32_e32 v85, v85
	v_mul_f32_e32 v76, v76, v84
	v_mul_f32_e32 v189, v76, v28
	v_mul_f32_e32 v76, v77, v85
	v_mul_f32_e32 v190, v76, v29
	v_fma_f32 v29, v82, s100, v211
	v_exp_f32_e32 v29, v29
	v_add_f32_e32 v76, v206, v78
	v_fma_f32 v78, v83, s100, v211
	v_add_f32_e32 v29, 1.0, v29
	v_rcp_f32_e32 v29, v29
	v_exp_f32_e32 v78, v78
	v_mul_f32_e32 v76, 0xbfb8aa3b, v76
	v_exp_f32_e32 v76, v76
	v_mul_f32_e32 v29, v207, v29
	v_mul_f32_e32 v29, 0x3fb8aa3b, v29
	v_add_f32_e32 v78, 1.0, v78
	v_exp_f32_e32 v29, v29
	v_rcp_f32_e32 v78, v78
	v_add_f32_e32 v76, 1.0, v76
	v_rcp_f32_e32 v76, v76
	v_fma_f32 v82, -v29, v29, 1.0
	v_mul_f32_e32 v78, v207, v78
	v_max_f32_e32 v82, 0, v82
	v_mul_f32_e32 v78, 0x3fb8aa3b, v78
	v_sqrt_f32_e32 v82, v82
	v_fma_f32 v79, v79, s100, v241
	v_exp_f32_e32 v78, v78
	v_exp_f32_e32 v79, v79
	v_mul_f32_e32 v76, v76, v82
	v_mul_f32_e32 v191, v76, v30
	v_fma_f32 v82, -v78, v78, 1.0
	v_add_f32_e32 v79, 1.0, v79
	v_max_f32_e32 v82, 0, v82
	v_rcp_f32_e32 v79, v79
	v_sqrt_f32_e32 v82, v82
	v_fma_f32 v68, v68, s100, v241
	v_exp_f32_e32 v68, v68
	v_mul_f32_e32 v76, v79, v82
	v_mul_f32_e32 v193, v76, v31
	v_fma_f32 v31, v72, s100, v211
	v_exp_f32_e32 v31, v31
	v_fma_f32 v72, v73, s100, v211
	v_exp_f32_e32 v72, v72
	v_add_f32_e32 v31, 1.0, v31
	v_rcp_f32_e32 v31, v31
	v_add_f32_e32 v68, 1.0, v68
	v_add_f32_e32 v72, 1.0, v72
	v_rcp_f32_e32 v72, v72
	v_mul_f32_e32 v31, v207, v31
	v_mul_f32_e32 v31, 0x3fb8aa3b, v31
	v_exp_f32_e32 v31, v31
	v_mul_f32_e32 v72, v207, v72
	v_mul_f32_e32 v72, 0x3fb8aa3b, v72
	v_fma_f32 v73, -v31, v31, 1.0
	v_max_f32_e32 v73, 0, v73
	v_rcp_f32_e32 v68, v68
	v_sqrt_f32_e32 v73, v73
	v_fma_f32 v69, v69, s100, v241
	v_exp_f32_e32 v72, v72
	v_exp_f32_e32 v69, v69
	v_mul_f32_e32 v68, v68, v73
	v_fma_f32 v28, 0, v80, v189
	v_fma_f32 v73, -v72, v72, 1.0
	v_add_f32_e32 v69, 1.0, v69
	v_max_f32_e32 v73, 0, v73
	v_rcp_f32_e32 v69, v69
	v_sqrt_f32_e32 v73, v73
	v_fma_f32 v28, v81, v28, v190
	v_mul_f32_e32 v77, v80, v81
	v_fma_f32 v28, v29, v28, v191
	v_mul_f32_e32 v30, v29, v77
	v_fma_f32 v28, v78, v28, v193
	v_mul_f32_e32 v30, v78, v30
	v_mul_f32_e32 v194, v68, v20
	v_fma_f32 v20, v28, v31, v194
	v_mul_f32_e32 v28, v30, v31
	v_mul_f32_e32 v30, v69, v73
	v_mul_f32_e32 v195, v30, v21
	v_fma_f32 v21, v74, s100, v211
	v_exp_f32_e32 v21, v21
	v_fma_f32 v68, v75, s100, v211
	v_exp_f32_e32 v68, v68
	v_add_f32_e32 v21, 1.0, v21
	v_rcp_f32_e32 v21, v21
	v_add_f32_e32 v68, 1.0, v68
	v_fma_f32 v30, v70, s100, v241
	v_mul_f32_e32 v21, v207, v21
	v_mul_f32_e32 v21, 0x3fb8aa3b, v21
	v_exp_f32_e32 v21, v21
	v_rcp_f32_e32 v68, v68
	v_exp_f32_e32 v30, v30
	v_fma_f32 v69, -v21, v21, 1.0
	v_mul_f32_e32 v68, v207, v68
	v_add_f32_e32 v30, 1.0, v30
	v_max_f32_e32 v69, 0, v69
	v_fma_f32 v70, v71, s100, v241
	v_mul_f32_e32 v68, 0x3fb8aa3b, v68
	v_rcp_f32_e32 v30, v30
	v_sqrt_f32_e32 v69, v69
	v_exp_f32_e32 v70, v70
	v_exp_f32_e32 v68, v68
	v_mul_f32_e32 v28, v72, v28
	v_mul_f32_e32 v30, v30, v69
	v_add_f32_e32 v69, 1.0, v70
	v_fma_f32 v70, -v68, v68, 1.0
	v_max_f32_e32 v70, 0, v70
	v_rcp_f32_e32 v69, v69
	v_sqrt_f32_e32 v70, v70
	v_mul_f32_e32 v196, v30, v22
	v_mul_f32_e32 v22, v21, v28
	v_mul_f32_e32 v28, v69, v70
	v_mul_f32_e32 v197, v28, v23
	v_fma_f32 v23, v32, s100, v211
	v_exp_f32_e32 v23, v23
	v_fma_f32 v28, v33, s100, v211
	v_exp_f32_e32 v28, v28
	v_add_f32_e32 v23, 1.0, v23
	v_rcp_f32_e32 v23, v23
	v_fma_f32 v24, v24, s100, v241
	v_add_f32_e32 v28, 1.0, v28
	v_rcp_f32_e32 v28, v28
	v_mul_f32_e32 v23, v207, v23
	v_mul_f32_e32 v23, 0x3fb8aa3b, v23
	v_exp_f32_e32 v23, v23
	v_exp_f32_e32 v24, v24
	v_mul_f32_e32 v28, v207, v28
	v_fma_f32 v30, -v23, v23, 1.0
	v_add_f32_e32 v24, 1.0, v24
	v_max_f32_e32 v30, 0, v30
	v_mul_f32_e32 v28, 0x3fb8aa3b, v28
	v_rcp_f32_e32 v24, v24
	v_sqrt_f32_e32 v30, v30
	v_fma_f32 v25, v25, s100, v241
	v_exp_f32_e32 v28, v28
	v_exp_f32_e32 v25, v25
	v_mul_f32_e32 v24, v24, v30
	v_fma_f32 v20, v72, v20, v195
	v_fma_f32 v30, -v28, v28, 1.0
	v_add_f32_e32 v25, 1.0, v25
	v_max_f32_e32 v30, 0, v30
	v_rcp_f32_e32 v25, v25
	v_sqrt_f32_e32 v30, v30
	v_fma_f32 v20, v21, v20, v196
	v_fma_f32 v20, v68, v20, v197
	v_mul_f32_e32 v22, v68, v22
	v_mul_f32_e32 v199, v24, v8
	v_fma_f32 v8, v20, v23, v199
	v_mul_f32_e32 v20, v22, v23
	v_mul_f32_e32 v22, v25, v30
	v_mul_f32_e32 v201, v22, v9
	v_fma_f32 v9, v34, s100, v211
	v_exp_f32_e32 v9, v9
	v_fma_f32 v22, v26, s100, v241
	v_exp_f32_e32 v22, v22
	v_add_f32_e32 v9, 1.0, v9
	v_rcp_f32_e32 v9, v9
	v_add_f32_e32 v22, 1.0, v22
	v_rcp_f32_e32 v22, v22
	v_mul_f32_e32 v9, v207, v9
	v_mul_f32_e32 v9, 0x3fb8aa3b, v9
	v_exp_f32_e32 v24, v9
; #define LAS __attribute__((address_space(3)))
; __device__ __forceinline__ unsigned cvt_pk_bf16(float lo, float hi) { unsigned r; asm volatile("v_cvt_pk_bf16_f32 %0, %1, %2" : "=v"(r) : "v"(lo), "v"(hi)); return r; }
; __device__ __forceinline__ float bf2f(unsigned short b) { return __uint_as_float(((unsigned)b) << 16); }
; __device__ __forceinline__ float fsig(float x) { return __builtin_amdgcn_rcpf(1.0f + __expf(-x)); }
; template <bool PASS2>
; __device__ __forceinline__ void lru_item(const Frame& F, const Args& a, int item) {
;     ...
;             for (int e = 0; e < 16; ++e) { const int ee = dir ? 15 - e : e; const int rt = ee >> 2, j = ee & 3;
;                 const float rg = fsig(ar[rt][j] + ba), ig = fsig(ai[rt][j] + bi); const float la = logu * rg; const float av = __expf(la);
;                 const float mult = (t0 + tl0 + ee == tstart) ? 1.0f : __builtin_amdgcn_sqrtf(fmaxf(1.0f - av * av, 0.f)); const float bv = mult * ig * ax[rt][j];
;                 ar[rt][j] = av; ai[rt][j] = bv; B16 = av * B16 + bv; A16 = av * A16; }
;             const int pos = dir ? 3 - fq : fq;
;             float PA = 1.f, PB = 0.f, QA = 1.f, QB = 0.f;
; #pragma unroll
;             for (int i = 0; i < 4; ++i) { const int k = dir ? 3 - i : i; const float Ak = __shfl(A16, fr + 16 * k), Bk = __shfl(B16, fr + 16 * k);
;                 if (i < pos) { PB = Ak * PB + Bk; PA = Ak * PA; }
;                 QB = Ak * QB + Bk; QA = Ak * QA; }
;             if (PASS2) {
;                 float h = PA * hc + PB;
; #pragma unroll
;                 for (int e = 0; e < 16; ++e) { const int ee = dir ? 15 - e : e; const int rt = ee >> 2, j = ee & 3; h = ar[rt][j] * h + ai[rt][j];
;                     if (dir == 0) hf[3][rt][j] = h;
;                     else { LAS unsigned short* yp = (LAS unsigned short*)(R0 + (tl0 + ee) * AT_PITCH + 2 * c); const float yb = bf2f(*yp);
;                         const float u2 = 1.5957691216057308f * (yb + 0.044715f * yb * yb * yb);
;                         const float y = (hf[3][rt][j] + h) * yb * fsig(u2);
;                         *yp = (unsigned short)(cvt_pk_bf16(y, 0.f) & 0xffffu); } }
;                 hc = QA * hc + QB;
;             } else { TB = QA * TB + QB; TA = QA * TA; }
	v_fma_f32 v9, v35, s100, v211
	v_exp_f32_e32 v9, v9
	v_fma_f32 v25, -v24, v24, 1.0
	v_max_f32_e32 v25, 0, v25
	v_sqrt_f32_e32 v25, v25
	v_add_f32_e32 v9, 1.0, v9
	v_rcp_f32_e32 v9, v9
	v_fma_f32 v26, v27, s100, v241
	v_exp_f32_e32 v26, v26
	v_mul_f32_e32 v9, v207, v9
	v_mul_f32_e32 v9, 0x3fb8aa3b, v9
	v_exp_f32_e32 v27, v9
	v_mul_f32_e32 v9, v22, v25
	v_add_f32_e32 v22, 1.0, v26
	v_rcp_f32_e32 v22, v22
	v_fma_f32 v25, -v27, v27, 1.0
	v_max_f32_e32 v25, 0, v25
	v_sqrt_f32_e32 v25, v25
	v_mul_f32_e32 v198, v9, v10
	v_fma_f32 v13, v13, s100, v241
	v_exp_f32_e32 v13, v13
	v_mul_f32_e32 v10, v22, v25
	v_mul_f32_e32 v200, v10, v11
	v_fma_f32 v10, v16, s100, v211
	v_exp_f32_e32 v10, v10
	v_add_f32_e32 v11, v206, v12
	v_fma_f32 v12, v17, s100, v211
	v_add_f32_e32 v10, 1.0, v10
	v_rcp_f32_e32 v10, v10
	v_exp_f32_e32 v12, v12
	v_mul_f32_e32 v11, 0xbfb8aa3b, v11
	v_exp_f32_e32 v11, v11
	v_mul_f32_e32 v10, v207, v10
	v_mul_f32_e32 v10, 0x3fb8aa3b, v10
	v_add_f32_e32 v12, 1.0, v12
	v_exp_f32_e32 v10, v10
	v_rcp_f32_e32 v12, v12
	v_add_f32_e32 v11, 1.0, v11
	v_rcp_f32_e32 v11, v11
	v_fma_f32 v16, -v10, v10, 1.0
	v_mul_f32_e32 v12, v207, v12
	v_max_f32_e32 v16, 0, v16
	v_mul_f32_e32 v12, 0x3fb8aa3b, v12
	v_sqrt_f32_e32 v16, v16
	v_exp_f32_e32 v12, v12
	v_add_f32_e32 v13, 1.0, v13
	v_rcp_f32_e32 v13, v13
	v_mul_f32_e32 v11, v11, v16
	v_fma_f32 v16, -v12, v12, 1.0
	v_max_f32_e32 v16, 0, v16
	v_sqrt_f32_e32 v16, v16
	v_fma_f32 v8, v28, v8, v201
	v_mul_f32_e32 v20, v28, v20
	v_fma_f32 v8, v24, v8, v198
	v_mul_f32_e32 v9, v24, v20
	v_fma_f32 v8, v27, v8, v200
	v_mul_f32_e32 v9, v27, v9
	v_mul_f32_e32 v202, v11, v4
	v_fma_f32 v4, v8, v10, v202
	v_mul_f32_e32 v8, v9, v10
	v_mul_f32_e32 v9, v13, v16
	v_mul_f32_e32 v203, v9, v5
	v_fma_f32 v5, v18, s100, v211
	v_exp_f32_e32 v5, v5
	v_fma_f32 v9, v14, s100, v241
	v_exp_f32_e32 v9, v9
	v_add_f32_e32 v5, 1.0, v5
	v_rcp_f32_e32 v5, v5
	v_add_f32_e32 v9, 1.0, v9
	v_fma_f32 v14, v15, s100, v241
	v_mul_f32_e32 v5, v207, v5
	v_mul_f32_e32 v5, 0x3fb8aa3b, v5
	v_exp_f32_e32 v11, v5
	v_fma_f32 v5, v19, s100, v211
	v_exp_f32_e32 v5, v5
	v_fma_f32 v13, -v11, v11, 1.0
	v_max_f32_e32 v13, 0, v13
	v_rcp_f32_e32 v9, v9
	v_add_f32_e32 v5, 1.0, v5
	v_rcp_f32_e32 v5, v5
	v_sqrt_f32_e32 v13, v13
	v_exp_f32_e32 v14, v14
	v_fma_f32 v4, v12, v4, v203
	v_mul_f32_e32 v5, v207, v5
	v_mul_f32_e32 v5, 0x3fb8aa3b, v5
	v_exp_f32_e32 v5, v5
	v_mul_f32_e32 v9, v9, v13
	v_add_f32_e32 v13, 1.0, v14
	v_rcp_f32_e32 v13, v13
	v_fma_f32 v14, -v5, v5, 1.0
	v_max_f32_e32 v14, 0, v14
	v_sqrt_f32_e32 v14, v14
	v_mul_f32_e32 v8, v12, v8
	v_mul_f32_e32 v205, v9, v6
	v_fma_f32 v9, v11, v4, v205
	v_mul_f32_e32 v15, v11, v8
	v_mul_f32_e32 v8, v13, v14
	v_mov_b32_e32 v4, v7
	v_pk_mul_f32 v[124:125], v[8:9], v[4:5]
	s_add_i32 s49, s49, 64
	v_pk_fma_f32 v[6:7], v[8:9], v[4:5], v[124:125] op_sel:[0,0,1] op_sel_hi:[1,1,0]
	v_mul_f32_e32 v4, v5, v15
	ds_bpermute_b32 v7, v140, v4
	ds_bpermute_b32 v13, v140, v6
	ds_bpermute_b32 v16, v128, v4
	ds_bpermute_b32 v17, v128, v6
	ds_bpermute_b32 v8, v129, v4
	ds_bpermute_b32 v18, v129, v6
	s_waitcnt lgkmcnt(4)
	v_fmac_f32_e32 v13, 0, v7
	v_cndmask_b32_e64 v14, v7, 1.0, s[0:1]
	v_cndmask_b32_e64 v15, v13, 0, s[0:1]
	ds_bpermute_b32 v9, v130, v4
	s_waitcnt lgkmcnt(3)
	v_fma_f32 v4, v15, v16, v17
	v_mul_f32_e32 v19, v14, v16
	v_cndmask_b32_e64 v14, v14, v19, s[16:17]
	v_cndmask_b32_e64 v4, v15, v4, s[16:17]
	v_fmac_f32_e32 v17, v13, v16
	s_waitcnt lgkmcnt(1)
	v_fma_f32 v13, v4, v8, v18
	v_mul_f32_e32 v15, v14, v8
	v_cndmask_b32_e64 v14, v14, v15, s[4:5]
	v_cndmask_b32_e64 v4, v4, v13, s[4:5]
	v_fmac_f32_e32 v4, v210, v14
	v_fmac_f32_e32 v189, v80, v4
	v_fmac_f32_e32 v190, v81, v189
	v_fmac_f32_e32 v191, v29, v190
	v_fmac_f32_e32 v193, v78, v191
	v_fmac_f32_e32 v194, v31, v193
	v_fmac_f32_e32 v195, v72, v194
	v_fmac_f32_e32 v196, v21, v195
	v_fmac_f32_e32 v197, v68, v196
	v_fmac_f32_e32 v199, v23, v197
	v_fmac_f32_e32 v201, v28, v199
	v_fmac_f32_e32 v198, v24, v201
	v_fmac_f32_e32 v200, v27, v198
	ds_bpermute_b32 v6, v130, v6
	v_fmac_f32_e32 v202, v10, v200
	v_fmac_f32_e32 v203, v12, v202
	v_mul_f32_e32 v13, v17, v8
	v_fmac_f32_e32 v205, v11, v203
	v_fmac_f32_e32 v124, v5, v205
	v_mul_f32_e32 v4, v7, v16
	v_add_f32_e32 v5, v13, v18
	s_waitcnt lgkmcnt(1)
	v_pk_mul_f32 v[4:5], v[4:5], v[8:9]
	s_cmpk_lg_i32 s49, 0x100
	v_mul_f32_e32 v4, v4, v9
	s_waitcnt lgkmcnt(0)
	v_add_f32_e32 v14, v5, v6
	v_fmac_f32_e32 v14, v210, v4
	v_add_u32_e32 v209, 0x4400, v209
	s_cbranch_scc0 .LBB0_742
	v_mov_b32_e32 v4, v163
	v_mov_b32_e32 v5, v164
	v_mov_b32_e32 v6, v165
	v_mov_b32_e32 v7, v166
	v_mov_b32_e32 v8, v167
	v_mov_b32_e32 v9, v168
	v_mov_b32_e32 v10, v169
	v_mov_b32_e32 v11, v170
	v_mov_b32_e32 v12, v171
	v_mov_b32_e32 v13, v172
	v_mov_b32_e32 v147, v188
	v_mov_b32_e32 v148, v187
	v_mov_b32_e32 v149, v186
	v_mov_b32_e32 v150, v185
	v_mov_b32_e32 v151, v184
	v_mov_b32_e32 v152, v183
	v_mov_b32_e32 v153, v182
	v_mov_b32_e32 v154, v181
	v_mov_b32_e32 v155, v180
	v_mov_b32_e32 v156, v179
	v_mov_b32_e32 v157, v178
	v_mov_b32_e32 v158, v177
	v_mov_b32_e32 v159, v176
	v_mov_b32_e32 v160, v175
	v_mov_b32_e32 v161, v174
	v_mov_b32_e32 v162, v173
	v_mov_b32_e32 v163, v201
	v_mov_b32_e32 v164, v199
	v_mov_b32_e32 v165, v197
	v_mov_b32_e32 v166, v196
	v_mov_b32_e32 v167, v195
	v_mov_b32_e32 v168, v194
	v_mov_b32_e32 v169, v193
	v_mov_b32_e32 v170, v191
	v_mov_b32_e32 v171, v190
	v_mov_b32_e32 v172, v189
	v_mov_b32_e32 v210, v14
	s_branch .LBB0_708

; __device__ __forceinline__ float fsig(float x) { return __builtin_amdgcn_rcpf(1.0f + __expf(-x)); }
; template <bool PASS2>
; __device__ __forceinline__ void lru_item(const Frame& F, const Args& a, int item) {
;     ...
;             for (int e = 0; e < 16; ++e) { const int ee = dir ? 15 - e : e; const int rt = ee >> 2, j = ee & 3;
;                 const float rg = fsig(ar[rt][j] + ba), ig = fsig(ai[rt][j] + bi); const float la = logu * rg; const float av = __expf(la);
;                 const float mult = (t0 + tl0 + ee == tstart) ? 1.0f : __builtin_amdgcn_sqrtf(fmaxf(1.0f - av * av, 0.f)); const float bv = mult * ig * ax[rt][j];
;                 ar[rt][j] = av; ai[rt][j] = bv; B16 = av * B16 + bv; A16 = av * A16; }
.LBB0_745:
	s_nop 3
	v_fma_f32 v83, v83, s100, v211
	v_exp_f32_e32 v83, v83
	v_fma_f32 v79, v79, s100, v241
	v_exp_f32_e32 v79, v79
	v_add_f32_e32 v83, 1.0, v83
	v_rcp_f32_e32 v83, v83
	s_xor_b32 s3, s2, 0xc0
	v_add_f32_e32 v79, 1.0, v79
	v_mul_f32_e32 v83, v126, v83
	v_mul_f32_e32 v83, 0x3fb8aa3b, v83
	v_exp_f32_e32 v83, v83
	v_or_b32_e32 v84, s3, v105
	v_fma_f32 v82, v82, s100, v211
	v_rcp_f32_e32 v79, v79
	v_fma_f32 v86, -v83, v83, 1.0
	v_max_f32_e32 v86, 0, v86
	v_sqrt_f32_e32 v86, v86
	v_add_u32_e32 v85, s74, v84
	v_exp_f32_e32 v82, v82
	s_movk_i32 s3, 0xff0
	v_cmp_ne_u32_e32 vcc, s3, v85
	v_fma_f32 v81, v81, s100, v211
	v_cndmask_b32_e32 v85, 1.0, v86, vcc
	v_mul_f32_e32 v79, v79, v85
	v_mul_f32_e32 v75, v79, v75
	v_add_f32_e32 v79, 1.0, v82
	v_rcp_f32_e32 v79, v79
	v_exp_f32_e32 v81, v81
	v_fma_f32 v78, v78, s100, v241
	v_mul_f32_e32 v79, v126, v79
	v_mul_f32_e32 v79, 0x3fb8aa3b, v79
	v_add_f32_e32 v81, 1.0, v81
	v_exp_f32_e32 v79, v79
	v_rcp_f32_e32 v81, v81
	v_exp_f32_e32 v78, v78
	v_fma_f32 v85, -v79, v79, 1.0
	v_mul_f32_e32 v81, v126, v81
	v_add_f32_e32 v78, 1.0, v78
	v_max_f32_e32 v85, 0, v85
	v_mul_f32_e32 v81, 0x3fb8aa3b, v81
	v_rcp_f32_e32 v78, v78
	v_sqrt_f32_e32 v85, v85
	v_fma_f32 v77, v77, s100, v241
	v_exp_f32_e32 v81, v81
	v_exp_f32_e32 v77, v77
	v_mul_f32_e32 v78, v78, v85
	v_fma_f32 v82, 0, v83, v75
	v_fma_f32 v85, -v81, v81, 1.0
	v_add_f32_e32 v77, 1.0, v77
	v_max_f32_e32 v85, 0, v85
	v_rcp_f32_e32 v77, v77
	v_sqrt_f32_e32 v85, v85
	v_mul_f32_e32 v74, v78, v74
	v_fma_f32 v78, v79, v82, v74
	v_mul_f32_e32 v77, v77, v85
	v_mul_f32_e32 v73, v77, v73
	v_fma_f32 v77, v81, v78, v73
	v_fma_f32 v78, v80, s100, v211
	v_exp_f32_e32 v78, v78
	v_fma_f32 v71, v71, s100, v211
	v_exp_f32_e32 v71, v71
	v_add_f32_e32 v78, 1.0, v78
	v_rcp_f32_e32 v78, v78
	v_add_f32_e32 v71, 1.0, v71
	v_fma_f32 v76, v76, s100, v241
	v_rcp_f32_e32 v71, v71
	v_mul_f32_e32 v78, v126, v78
	v_mul_f32_e32 v78, 0x3fb8aa3b, v78
	v_exp_f32_e32 v78, v78
	v_exp_f32_e32 v76, v76
	v_fma_f32 v70, v70, s100, v211
	v_mul_f32_e32 v82, v83, v79
	v_exp_f32_e32 v70, v70
	v_mul_f32_e32 v80, v81, v82
	v_fma_f32 v82, -v78, v78, 1.0
	v_mul_f32_e32 v71, v126, v71
	v_add_f32_e32 v76, 1.0, v76
	v_max_f32_e32 v82, 0, v82
	v_mul_f32_e32 v71, 0x3fb8aa3b, v71
	v_rcp_f32_e32 v76, v76
	v_sqrt_f32_e32 v82, v82
	v_fma_f32 v67, v67, s100, v241
	v_exp_f32_e32 v71, v71
	v_exp_f32_e32 v67, v67
	v_add_f32_e32 v70, 1.0, v70
	v_rcp_f32_e32 v70, v70
	v_fma_f32 v69, v69, s100, v211
	v_exp_f32_e32 v69, v69
	v_mul_f32_e32 v76, v76, v82
	v_fma_f32 v82, -v71, v71, 1.0
	v_add_f32_e32 v67, 1.0, v67
	v_max_f32_e32 v82, 0, v82
	v_rcp_f32_e32 v67, v67
	v_sqrt_f32_e32 v82, v82
	v_mul_f32_e32 v70, v126, v70
	v_mul_f32_e32 v70, 0x3fb8aa3b, v70
	v_add_f32_e32 v69, 1.0, v69
	v_fma_f32 v66, v66, s100, v241
	v_exp_f32_e32 v70, v70
	v_rcp_f32_e32 v69, v69
	v_exp_f32_e32 v66, v66
	v_mul_f32_e32 v72, v76, v72
	v_mul_f32_e32 v67, v67, v82
	v_fma_f32 v76, v78, v77, v72
	v_mul_f32_e32 v77, v78, v80
	v_mul_f32_e32 v63, v67, v63
	v_fma_f32 v67, v71, v76, v63
	v_mul_f32_e32 v76, v71, v77
	v_fma_f32 v77, -v70, v70, 1.0
	v_mul_f32_e32 v69, v126, v69
	v_add_f32_e32 v66, 1.0, v66
	v_max_f32_e32 v77, 0, v77
	v_mul_f32_e32 v69, 0x3fb8aa3b, v69
	v_rcp_f32_e32 v66, v66
	v_sqrt_f32_e32 v77, v77
	v_fma_f32 v65, v65, s100, v241
	v_exp_f32_e32 v69, v69
	v_exp_f32_e32 v65, v65
	v_mul_f32_e32 v66, v66, v77
	v_mul_f32_e32 v62, v66, v62
	v_fma_f32 v77, -v69, v69, 1.0
	v_add_f32_e32 v65, 1.0, v65
	v_max_f32_e32 v77, 0, v77
	v_rcp_f32_e32 v65, v65
	v_sqrt_f32_e32 v77, v77
	v_fma_f32 v66, v70, v67, v62
	v_fma_f32 v59, v59, s100, v211
	v_mul_f32_e32 v65, v65, v77
	v_mul_f32_e32 v61, v65, v61
	v_fma_f32 v65, v69, v66, v61
	v_fma_f32 v66, v68, s100, v211
	v_exp_f32_e32 v66, v66
	v_exp_f32_e32 v59, v59
	v_fma_f32 v64, v64, s100, v241
	v_add_f32_e32 v66, 1.0, v66
	v_rcp_f32_e32 v66, v66
	v_add_f32_e32 v59, 1.0, v59
	v_rcp_f32_e32 v59, v59
	v_exp_f32_e32 v64, v64
	v_mul_f32_e32 v66, v126, v66
	v_mul_f32_e32 v66, 0x3fb8aa3b, v66
	v_exp_f32_e32 v66, v66
	v_mul_f32_e32 v59, v126, v59
	v_add_f32_e32 v64, 1.0, v64
	v_fma_f32 v68, -v66, v66, 1.0
	v_max_f32_e32 v68, 0, v68
	v_mul_f32_e32 v59, 0x3fb8aa3b, v59
	v_rcp_f32_e32 v64, v64
	v_sqrt_f32_e32 v68, v68
	v_fma_f32 v55, v55, s100, v241
	v_exp_f32_e32 v59, v59
	v_exp_f32_e32 v55, v55
	v_mul_f32_e32 v64, v64, v68
	v_mul_f32_e32 v67, v70, v76
	v_fma_f32 v68, -v59, v59, 1.0
	v_add_f32_e32 v55, 1.0, v55
	v_max_f32_e32 v68, 0, v68
	v_rcp_f32_e32 v55, v55
	v_sqrt_f32_e32 v68, v68
	v_mul_f32_e32 v67, v69, v67
	v_mul_f32_e32 v60, v64, v60
	v_fma_f32 v64, v66, v65, v60
	v_mul_f32_e32 v55, v55, v68
	v_mul_f32_e32 v65, v66, v67
	v_mul_f32_e32 v67, v55, v51
	v_fma_f32 v55, v58, s100, v211
	v_exp_f32_e32 v55, v55
	v_fma_f32 v51, v59, v64, v67
	v_fma_f32 v54, v54, s100, v241
	v_add_f32_e32 v55, 1.0, v55
	v_rcp_f32_e32 v55, v55
	v_exp_f32_e32 v54, v54
	v_mul_f32_e32 v58, v59, v65
	v_mul_f32_e32 v55, v126, v55
	v_mul_f32_e32 v55, 0x3fb8aa3b, v55
	v_exp_f32_e32 v64, v55
	v_fma_f32 v55, v57, s100, v211
	v_exp_f32_e32 v55, v55
	v_fma_f32 v53, v53, s100, v241
	v_exp_f32_e32 v53, v53
	v_fma_f32 v57, -v64, v64, 1.0
	v_add_f32_e32 v55, 1.0, v55
	v_rcp_f32_e32 v55, v55
	v_add_f32_e32 v54, 1.0, v54
	v_max_f32_e32 v57, 0, v57
	v_rcp_f32_e32 v54, v54
	v_mul_f32_e32 v55, v126, v55
	v_mul_f32_e32 v55, 0x3fb8aa3b, v55
	v_exp_f32_e32 v65, v55
	v_sqrt_f32_e32 v57, v57
	v_add_f32_e32 v53, 1.0, v53
	v_rcp_f32_e32 v53, v53
	v_fma_f32 v55, -v65, v65, 1.0
	v_max_f32_e32 v55, 0, v55
	v_sqrt_f32_e32 v55, v55
	v_mul_f32_e32 v54, v54, v57
	v_mul_f32_e32 v57, v54, v50
	v_fma_f32 v50, v64, v51, v57
	v_mul_f32_e32 v53, v53, v55
; #define LAS __attribute__((address_space(3)))
; __device__ __forceinline__ unsigned cvt_pk_bf16(float lo, float hi) { unsigned r; asm volatile("v_cvt_pk_bf16_f32 %0, %1, %2" : "=v"(r) : "v"(lo), "v"(hi)); return r; }
; __device__ __forceinline__ float bf2f(unsigned short b) { return __uint_as_float(((unsigned)b) << 16); }
; __device__ __forceinline__ float fsig(float x) { return __builtin_amdgcn_rcpf(1.0f + __expf(-x)); }
; template <bool PASS2>
; __device__ __forceinline__ void lru_item(const Frame& F, const Args& a, int item) {
;     ...
;             for (int e = 0; e < 16; ++e) { const int ee = dir ? 15 - e : e; const int rt = ee >> 2, j = ee & 3;
;                 const float rg = fsig(ar[rt][j] + ba), ig = fsig(ai[rt][j] + bi); const float la = logu * rg; const float av = __expf(la);
;                 const float mult = (t0 + tl0 + ee == tstart) ? 1.0f : __builtin_amdgcn_sqrtf(fmaxf(1.0f - av * av, 0.f)); const float bv = mult * ig * ax[rt][j];
;                 ar[rt][j] = av; ai[rt][j] = bv; B16 = av * B16 + bv; A16 = av * A16; }
;             const int pos = dir ? 3 - fq : fq;
;             float PA = 1.f, PB = 0.f, QA = 1.f, QB = 0.f;
; #pragma unroll
;             for (int i = 0; i < 4; ++i) { const int k = dir ? 3 - i : i; const float Ak = __shfl(A16, fr + 16 * k), Bk = __shfl(B16, fr + 16 * k);
;                 if (i < pos) { PB = Ak * PB + Bk; PA = Ak * PA; }
;                 QB = Ak * QB + Bk; QA = Ak * QA; }
;             if (PASS2) {
;                 float h = PA * hc + PB;
; #pragma unroll
;                 for (int e = 0; e < 16; ++e) { const int ee = dir ? 15 - e : e; const int rt = ee >> 2, j = ee & 3; h = ar[rt][j] * h + ai[rt][j];
;                     if (dir == 0) hf[3][rt][j] = h;
;                     else { LAS unsigned short* yp = (LAS unsigned short*)(R0 + (tl0 + ee) * AT_PITCH + 2 * c); const float yb = bf2f(*yp);
;                         const float u2 = 1.5957691216057308f * (yb + 0.044715f * yb * yb * yb);
;                         const float y = (hf[3][rt][j] + h) * yb * fsig(u2);
;                         *yp = (unsigned short)(cvt_pk_bf16(y, 0.f) & 0xffffu); } }
	v_mul_f32_e32 v51, v64, v58
	v_mul_f32_e32 v58, v53, v49
	v_fma_f32 v49, v65, v50, v58
	v_fma_f32 v50, v56, s100, v211
	v_exp_f32_e32 v50, v50
	v_fma_f32 v47, v47, s100, v211
	v_exp_f32_e32 v47, v47
	v_add_f32_e32 v50, 1.0, v50
	v_rcp_f32_e32 v50, v50
	v_add_f32_e32 v47, 1.0, v47
	v_fma_f32 v52, v52, s100, v241
	v_mul_f32_e32 v50, v126, v50
	v_mul_f32_e32 v50, 0x3fb8aa3b, v50
	v_exp_f32_e32 v56, v50
	v_rcp_f32_e32 v47, v47
	v_exp_f32_e32 v52, v52
	v_mul_f32_e32 v53, v65, v51
	v_fma_f32 v50, -v56, v56, 1.0
	v_mul_f32_e32 v47, v126, v47
	v_add_f32_e32 v51, 1.0, v52
	v_max_f32_e32 v50, 0, v50
	v_mul_f32_e32 v47, 0x3fb8aa3b, v47
	v_rcp_f32_e32 v51, v51
	v_sqrt_f32_e32 v50, v50
	v_fma_f32 v43, v43, s100, v241
	v_exp_f32_e32 v47, v47
	v_exp_f32_e32 v43, v43
	v_mul_f32_e32 v50, v51, v50
	v_mul_f32_e32 v68, v50, v48
	v_fma_f32 v51, -v47, v47, 1.0
	v_add_f32_e32 v43, 1.0, v43
	v_max_f32_e32 v51, 0, v51
	v_rcp_f32_e32 v43, v43
	v_sqrt_f32_e32 v52, v51
	v_fma_f32 v42, v42, s100, v241
	v_exp_f32_e32 v42, v42
	v_mul_f32_e32 v50, v43, v52
	v_fma_f32 v43, v46, s100, v211
	v_exp_f32_e32 v43, v43
	v_mov_b32_e32 v46, v39
	v_add_f32_e32 v42, 1.0, v42
	v_rcp_f32_e32 v42, v42
	v_add_f32_e32 v39, 1.0, v43
	v_rcp_f32_e32 v39, v39
	v_fma_f32 v51, v56, v49, v68
	v_fma_f32 v45, v45, s100, v211
	v_mul_f32_e32 v39, v126, v39
	v_mul_f32_e32 v39, 0x3fb8aa3b, v39
	v_exp_f32_e32 v39, v39
	v_pk_mul_f32 v[48:49], v[50:51], v[46:47]
	v_exp_f32_e32 v45, v45
	v_pk_fma_f32 v[50:51], v[50:51], v[46:47], v[48:49] op_sel_hi:[1,1,0]
	v_fma_f32 v43, -v39, v39, 1.0
	v_max_f32_e32 v43, 0, v43
	v_sqrt_f32_e32 v43, v43
	v_mul_f32_e32 v53, v56, v53
	v_mul_f32_e32 v46, v47, v53
	v_mul_f32_e32 v50, v42, v43
	v_pk_mul_f32 v[42:43], v[50:51], v[38:39]
	v_fma_f32 v44, v44, s100, v211
	v_pk_fma_f32 v[50:51], v[50:51], v[38:39], v[42:43] op_sel_hi:[1,1,0]
	v_add_f32_e32 v38, 1.0, v45
	v_rcp_f32_e32 v38, v38
	v_fma_f32 v41, v41, s100, v241
	v_exp_f32_e32 v41, v41
	v_mul_f32_e32 v38, v126, v38
	v_mul_f32_e32 v38, 0x3fb8aa3b, v38
	v_exp_f32_e32 v45, v38
	v_mul_f32_e32 v38, v39, v46
	v_exp_f32_e32 v46, v44
	v_mov_b32_e32 v44, v37
	v_fma_f32 v43, -v45, v45, 1.0
	v_add_f32_e32 v37, 1.0, v46
	v_rcp_f32_e32 v37, v37
	v_fma_f32 v40, v40, s100, v241
	v_add_f32_e32 v41, 1.0, v41
	v_max_f32_e32 v43, 0, v43
	v_mul_f32_e32 v37, v126, v37
	v_exp_f32_e32 v40, v40
	v_mul_f32_e32 v37, 0x3fb8aa3b, v37
	v_rcp_f32_e32 v41, v41
	v_sqrt_f32_e32 v43, v43
	v_exp_f32_e32 v37, v37
	v_add_f32_e32 v40, 1.0, v40
	v_mul_f32_e32 v38, v45, v38
	v_mul_f32_e32 v50, v41, v43
	v_rcp_f32_e32 v43, v40
	v_fma_f32 v40, -v37, v37, 1.0
	v_max_f32_e32 v40, 0, v40
	v_sqrt_f32_e32 v46, v40
	v_pk_mul_f32 v[40:41], v[50:51], v[44:45]
	s_add_i32 s2, s2, 64
	v_pk_fma_f32 v[52:53], v[50:51], v[44:45], v[40:41] op_sel_hi:[1,1,0]
	s_cmpk_lg_i32 s2, 0x100
	v_mul_f32_e32 v52, v43, v46
	v_pk_mul_f32 v[50:51], v[52:53], v[36:37]
	s_nop 0
	v_pk_fma_f32 v[54:55], v[52:53], v[36:37], v[50:51] op_sel:[0,0,1] op_sel_hi:[1,1,0]
	v_mad_u64_u32 v[52:53], s[30:31], v84, s50, v[120:121]
	v_mul_f32_e32 v36, v37, v38
	ds_read_u16 v38, v52 offset:4080
	ds_bpermute_b32 v41, v130, v36
	ds_bpermute_b32 v43, v130, v54
	ds_bpermute_b32 v49, v129, v36
	ds_bpermute_b32 v55, v129, v54
	s_waitcnt lgkmcnt(4)
	v_lshlrev_b32_e32 v51, 16, v38
	v_mul_f32_e32 v38, 0x3d372713, v51
	v_mul_f32_e32 v38, v38, v51
	v_fma_f32 v38, v38, v51, v51
	v_mul_f32_e32 v38, 0x3fcc422a, v38
	v_mul_f32_e32 v38, 0xbfb8aa3b, v38
	v_exp_f32_e32 v53, v38
	ds_bpermute_b32 v38, v128, v36
	ds_bpermute_b32 v76, v128, v54
	s_waitcnt lgkmcnt(4)
	v_fmac_f32_e32 v43, 0, v41
	v_cndmask_b32_e64 v44, v41, 1.0, s[4:5]
	v_cndmask_b32_e64 v46, v43, 0, s[4:5]
	s_waitcnt lgkmcnt(2)
	v_fma_f32 v77, v46, v49, v55
	v_mul_f32_e32 v80, v44, v49
	v_cndmask_b32_e64 v44, v44, v80, s[6:7]
	v_cndmask_b32_e64 v46, v46, v77, s[6:7]
	s_waitcnt lgkmcnt(0)
	v_fma_f32 v77, v46, v38, v76
	v_mul_f32_e32 v80, v44, v38
	v_add_f32_e32 v53, 1.0, v53
	v_cndmask_b32_e64 v44, v44, v80, s[0:1]
	v_cndmask_b32_e64 v46, v46, v77, s[0:1]
	v_rcp_f32_e32 v53, v53
	v_fmac_f32_e32 v46, v127, v44
	v_fmac_f32_e32 v75, v83, v46
	v_add_f32_e32 v44, v124, v75
	v_mul_f32_e32 v44, v44, v51
	v_mul_f32_e32 v44, v44, v53
	v_cvt_pk_bf16_f32 v44, v44, v97
	ds_read_u16 v46, v52 offset:3808
	ds_write_b16 v52, v44 offset:4080
	v_fmac_f32_e32 v74, v79, v75
	v_fmac_f32_e32 v73, v81, v74
	v_fmac_f32_e32 v72, v78, v73
	s_waitcnt lgkmcnt(1)
	v_lshlrev_b32_e32 v46, 16, v46
	v_mul_f32_e32 v51, 0x3d372713, v46
	v_mul_f32_e32 v51, v51, v46
	v_fma_f32 v51, v51, v46, v46
	v_mul_f32_e32 v51, 0x3fcc422a, v51
	v_mul_f32_e32 v51, 0xbfb8aa3b, v51
	v_exp_f32_e32 v51, v51
	v_fmac_f32_e32 v63, v71, v72
	v_fmac_f32_e32 v62, v70, v63
	v_fmac_f32_e32 v61, v69, v62
	v_add_f32_e32 v44, 1.0, v51
	v_rcp_f32_e32 v44, v44
	v_add_f32_e32 v51, v205, v74
	v_mul_f32_e32 v46, v51, v46
	v_fmac_f32_e32 v60, v66, v61
	v_mul_f32_e32 v44, v46, v44
	v_cvt_pk_bf16_f32 v44, v44, v97
	ds_read_u16 v46, v52 offset:3536
	ds_write_b16 v52, v44 offset:3808
	v_fmac_f32_e32 v67, v59, v60
	v_fmac_f32_e32 v57, v64, v67
	v_fmac_f32_e32 v58, v65, v57
	s_waitcnt lgkmcnt(1)
	v_lshlrev_b32_e32 v46, 16, v46
	v_mul_f32_e32 v51, 0x3d372713, v46
	v_mul_f32_e32 v51, v51, v46
	v_fma_f32 v51, v51, v46, v46
	v_mul_f32_e32 v51, 0x3fcc422a, v51
	v_mul_f32_e32 v51, 0xbfb8aa3b, v51
	v_exp_f32_e32 v51, v51
	v_fmac_f32_e32 v68, v56, v58
	v_fmac_f32_e32 v48, v47, v68
	v_add_f32_e32 v47, v193, v48
	v_add_f32_e32 v44, 1.0, v51
	v_rcp_f32_e32 v44, v44
	v_add_f32_e32 v51, v203, v73
	v_mul_f32_e32 v46, v51, v46
	v_fmac_f32_e32 v42, v39, v48
	v_mul_f32_e32 v44, v46, v44
	v_cvt_pk_bf16_f32 v44, v44, v97
	ds_read_u16 v46, v52 offset:3264
	ds_write_b16 v52, v44 offset:3536
	v_add_f32_e32 v39, v191, v42
	v_fmac_f32_e32 v40, v45, v42
	v_add_f32_e32 v42, v190, v40
	s_waitcnt lgkmcnt(1)
; #define LAS __attribute__((address_space(3)))
; __device__ __forceinline__ unsigned cvt_pk_bf16(float lo, float hi) { unsigned r; asm volatile("v_cvt_pk_bf16_f32 %0, %1, %2" : "=v"(r) : "v"(lo), "v"(hi)); return r; }
; __device__ __forceinline__ float bf2f(unsigned short b) { return __uint_as_float(((unsigned)b) << 16); }
; __device__ __forceinline__ float fsig(float x) { return __builtin_amdgcn_rcpf(1.0f + __expf(-x)); }
; template <bool PASS2>
; __device__ __forceinline__ void lru_item(const Frame& F, const Args& a, int item) {
;     ...
;                 for (int e = 0; e < 16; ++e) { const int ee = dir ? 15 - e : e; const int rt = ee >> 2, j = ee & 3; h = ar[rt][j] * h + ai[rt][j];
;                     if (dir == 0) hf[3][rt][j] = h;
;                     else { LAS unsigned short* yp = (LAS unsigned short*)(R0 + (tl0 + ee) * AT_PITCH + 2 * c); const float yb = bf2f(*yp);
;                         const float u2 = 1.5957691216057308f * (yb + 0.044715f * yb * yb * yb);
;                         const float y = (hf[3][rt][j] + h) * yb * fsig(u2);
;                         *yp = (unsigned short)(cvt_pk_bf16(y, 0.f) & 0xffffu); } }
;                 hc = QA * hc + QB;
;             } else { TB = QA * TB + QB; TA = QA * TA; }
;             if (PASS2 && dir == 1) {
; #pragma unroll
;                 for (int i1 = 0; i1 < 4; ++i1)
; #pragma unroll
;                     for (int i2 = 0; i2 < 4; ++i2) { hf[3][i1][i2] = hf[2][i1][i2]; hf[2][i1][i2] = hf[1][i1][i2]; hf[1][i1][i2] = hf[0][i1][i2]; } }
	v_lshlrev_b32_e32 v46, 16, v46
	v_mul_f32_e32 v51, 0x3d372713, v46
	v_mul_f32_e32 v51, v51, v46
	v_fma_f32 v51, v51, v46, v46
	v_mul_f32_e32 v51, 0x3fcc422a, v51
	v_mul_f32_e32 v51, 0xbfb8aa3b, v51
	v_exp_f32_e32 v51, v51
	v_fmac_f32_e32 v50, v37, v40
	v_add_f32_e32 v37, v189, v50
	ds_bpermute_b32 v45, v140, v54
	v_add_f32_e32 v44, 1.0, v51
	v_rcp_f32_e32 v44, v44
	v_add_f32_e32 v51, v202, v72
	v_mul_f32_e32 v46, v51, v46
	v_fmac_f32_e32 v55, v43, v49
	v_mul_f32_e32 v44, v46, v44
	v_cvt_pk_bf16_f32 v44, v44, v97
	ds_read_u16 v46, v52 offset:2992
	ds_write_b16 v52, v44 offset:3264
	v_mul_f32_e32 v43, v55, v38
	v_mov_b32_e32 v124, v133
	v_mov_b32_e32 v205, v143
	s_waitcnt lgkmcnt(1)
	v_lshlrev_b32_e32 v46, 16, v46
	v_mul_f32_e32 v51, 0x3d372713, v46
	v_mul_f32_e32 v51, v51, v46
	v_fma_f32 v51, v51, v46, v46
	v_mul_f32_e32 v51, 0x3fcc422a, v51
	v_mul_f32_e32 v51, 0xbfb8aa3b, v51
	v_exp_f32_e32 v51, v51
	v_mov_b32_e32 v203, v145
	v_mov_b32_e32 v202, v146
	v_mov_b32_e32 v193, v169
	v_add_f32_e32 v44, 1.0, v51
	v_rcp_f32_e32 v44, v44
	v_add_f32_e32 v51, v200, v63
	v_mul_f32_e32 v46, v51, v46
	v_mov_b32_e32 v200, v131
	v_mul_f32_e32 v44, v46, v44
	v_cvt_pk_bf16_f32 v44, v44, v97
	ds_read_u16 v46, v52 offset:2720
	ds_write_b16 v52, v44 offset:2992
	v_mov_b32_e32 v191, v170
	v_mov_b32_e32 v190, v171
	v_mov_b32_e32 v189, v172
	s_waitcnt lgkmcnt(1)
	v_lshlrev_b32_e32 v46, 16, v46
	v_mul_f32_e32 v51, 0x3d372713, v46
	v_mul_f32_e32 v51, v51, v46
	v_fma_f32 v51, v51, v46, v46
	v_mul_f32_e32 v51, 0x3fcc422a, v51
	v_mul_f32_e32 v51, 0xbfb8aa3b, v51
	v_exp_f32_e32 v51, v51
	v_mov_b32_e32 v133, v188
	v_mov_b32_e32 v143, v187
	v_mov_b32_e32 v145, v186
	v_add_f32_e32 v44, 1.0, v51
	v_rcp_f32_e32 v44, v44
	v_add_f32_e32 v51, v198, v62
	v_mul_f32_e32 v46, v51, v46
	v_mov_b32_e32 v198, v132
	v_mul_f32_e32 v44, v46, v44
	v_cvt_pk_bf16_f32 v44, v44, v97
	ds_read_u16 v46, v52 offset:2448
	ds_write_b16 v52, v44 offset:2720
	v_mov_b32_e32 v146, v185
	v_mov_b32_e32 v131, v184
	v_mov_b32_e32 v132, v183
	s_waitcnt lgkmcnt(1)
	v_lshlrev_b32_e32 v46, 16, v46
	v_mul_f32_e32 v51, 0x3d372713, v46
	v_mul_f32_e32 v51, v51, v46
	v_fma_f32 v51, v51, v46, v46
	v_mul_f32_e32 v51, 0x3fcc422a, v51
	v_mul_f32_e32 v51, 0xbfb8aa3b, v51
	v_exp_f32_e32 v51, v51
	v_mov_b32_e32 v169, v176
	v_mov_b32_e32 v170, v175
	v_mov_b32_e32 v171, v174
	v_add_f32_e32 v44, 1.0, v51
	v_rcp_f32_e32 v44, v44
	v_add_f32_e32 v51, v201, v61
	v_mul_f32_e32 v46, v51, v46
	v_mov_b32_e32 v201, v163
	v_mul_f32_e32 v44, v46, v44
	v_cvt_pk_bf16_f32 v44, v44, v97
	ds_read_u16 v46, v52 offset:2176
	ds_write_b16 v52, v44 offset:2448
	v_mov_b32_e32 v163, v182
	v_mov_b32_e32 v172, v173
	v_mov_b32_e32 v188, v147
	s_waitcnt lgkmcnt(1)
	v_lshlrev_b32_e32 v46, 16, v46
	v_mul_f32_e32 v51, 0x3d372713, v46
	v_mul_f32_e32 v51, v51, v46
	v_fma_f32 v51, v51, v46, v46
	v_mul_f32_e32 v51, 0x3fcc422a, v51
	v_mul_f32_e32 v51, 0xbfb8aa3b, v51
	v_exp_f32_e32 v51, v51
	v_mov_b32_e32 v187, v148
	v_mov_b32_e32 v186, v149
	v_mov_b32_e32 v185, v150
	v_add_f32_e32 v44, 1.0, v51
	v_rcp_f32_e32 v44, v44
	v_add_f32_e32 v51, v199, v60
	v_mul_f32_e32 v46, v51, v46
	v_mov_b32_e32 v199, v164
	v_mul_f32_e32 v44, v46, v44
	v_cvt_pk_bf16_f32 v44, v44, v97
	ds_read_u16 v46, v52 offset:1904
	ds_write_b16 v52, v44 offset:2176
	v_mov_b32_e32 v164, v181
	v_mov_b32_e32 v184, v151
	v_mov_b32_e32 v183, v152
	s_waitcnt lgkmcnt(1)
	v_lshlrev_b32_e32 v46, 16, v46
	v_mul_f32_e32 v51, 0x3d372713, v46
	v_mul_f32_e32 v51, v51, v46
	v_fma_f32 v51, v51, v46, v46
	v_mul_f32_e32 v51, 0x3fcc422a, v51
	v_mul_f32_e32 v51, 0xbfb8aa3b, v51
	v_exp_f32_e32 v51, v51
	v_mov_b32_e32 v182, v153
	v_mov_b32_e32 v181, v154
	v_mov_b32_e32 v176, v159
	v_add_f32_e32 v44, 1.0, v51
	v_rcp_f32_e32 v44, v44
	v_add_f32_e32 v51, v197, v67
	v_mul_f32_e32 v46, v51, v46
	v_mov_b32_e32 v197, v165
	v_mul_f32_e32 v44, v46, v44
	v_cvt_pk_bf16_f32 v44, v44, v97
	ds_read_u16 v46, v52 offset:1632
	ds_write_b16 v52, v44 offset:1904
	v_mov_b32_e32 v165, v180
	v_mov_b32_e32 v180, v155
	v_mov_b32_e32 v175, v160
	s_waitcnt lgkmcnt(1)
	v_lshlrev_b32_e32 v46, 16, v46
	v_mul_f32_e32 v51, 0x3d372713, v46
	v_mul_f32_e32 v51, v51, v46
	v_fma_f32 v51, v51, v46, v46
	v_mul_f32_e32 v51, 0x3fcc422a, v51
	v_mul_f32_e32 v51, 0xbfb8aa3b, v51
	v_exp_f32_e32 v51, v51
	v_mov_b32_e32 v174, v161
	v_mov_b32_e32 v173, v162
	v_add_f32_e32 v44, 1.0, v51
	v_rcp_f32_e32 v44, v44
	v_add_f32_e32 v51, v196, v57
	v_mul_f32_e32 v46, v51, v46
	v_mov_b32_e32 v196, v166
	v_mul_f32_e32 v44, v46, v44
	v_cvt_pk_bf16_f32 v44, v44, v97
	ds_read_u16 v46, v52 offset:1360
	ds_write_b16 v52, v44 offset:1632
	v_mov_b32_e32 v166, v179
	v_mov_b32_e32 v179, v156
	s_waitcnt lgkmcnt(1)
; #define LAS __attribute__((address_space(3)))
; __device__ __forceinline__ unsigned cvt_pk_bf16(float lo, float hi) { unsigned r; asm volatile("v_cvt_pk_bf16_f32 %0, %1, %2" : "=v"(r) : "v"(lo), "v"(hi)); return r; }
; __device__ __forceinline__ float bf2f(unsigned short b) { return __uint_as_float(((unsigned)b) << 16); }
; __device__ __forceinline__ float fsig(float x) { return __builtin_amdgcn_rcpf(1.0f + __expf(-x)); }
; template <bool PASS2>
; __device__ __forceinline__ void lru_item(const Frame& F, const Args& a, int item) {
;     ...
;                 for (int ks = 0; ks < 4; ++ks) { const bf16x8 xf = *(const LAS bf16x8*)(AT + (64 * s + 16 * rt + fr) * AT_PITCH + 64 * ks + 16 * fq);
;                     ar[rt] = __builtin_amdgcn_mfma_f32_16x16x32_bf16(xf, wrf[ks], ar[rt], 0, 0, 0); ai[rt] = __builtin_amdgcn_mfma_f32_16x16x32_bf16(xf, wif[ks], ai[rt], 0, 0, 0);
;                     if (ks == ks0) ax[rt] = __builtin_amdgcn_mfma_f32_16x16x32_bf16(xf, sel, ax[rt], 0, 0, 0); } }
;             const int tl0 = 64 * s + 16 * fq;
;             float A16 = 1.f, B16 = 0.f;
; #pragma unroll
;             for (int e = 0; e < 16; ++e) { const int ee = dir ? 15 - e : e; const int rt = ee >> 2, j = ee & 3;
;                 const float rg = fsig(ar[rt][j] + ba), ig = fsig(ai[rt][j] + bi); const float la = logu * rg; const float av = __expf(la);
;     ...
;                 for (int e = 0; e < 16; ++e) { const int ee = dir ? 15 - e : e; const int rt = ee >> 2, j = ee & 3; h = ar[rt][j] * h + ai[rt][j];
;                     if (dir == 0) hf[3][rt][j] = h;
;                     else { LAS unsigned short* yp = (LAS unsigned short*)(R0 + (tl0 + ee) * AT_PITCH + 2 * c); const float yb = bf2f(*yp);
;                         const float u2 = 1.5957691216057308f * (yb + 0.044715f * yb * yb * yb);
;                         const float y = (hf[3][rt][j] + h) * yb * fsig(u2);
;                         *yp = (unsigned short)(cvt_pk_bf16(y, 0.f) & 0xffffu); } }
;                 hc = QA * hc + QB;
;             } else { TB = QA * TB + QB; TA = QA * TA; }
;             if (PASS2 && dir == 1) {
; #pragma unroll
;                 for (int i1 = 0; i1 < 4; ++i1)
; #pragma unroll
;                     for (int i2 = 0; i2 < 4; ++i2) { hf[3][i1][i2] = hf[2][i1][i2]; hf[2][i1][i2] = hf[1][i1][i2]; hf[1][i1][i2] = hf[0][i1][i2]; } }
	v_lshlrev_b32_e32 v46, 16, v46
	v_mul_f32_e32 v51, 0x3d372713, v46
	v_mul_f32_e32 v51, v51, v46
	v_fma_f32 v51, v51, v46, v46
	v_mul_f32_e32 v51, 0x3fcc422a, v51
	v_mul_f32_e32 v51, 0xbfb8aa3b, v51
	v_exp_f32_e32 v51, v51
	s_nop 0
	v_add_f32_e32 v44, 1.0, v51
	v_rcp_f32_e32 v44, v44
	v_add_f32_e32 v51, v195, v58
	v_mul_f32_e32 v46, v51, v46
	v_mov_b32_e32 v195, v167
	v_mul_f32_e32 v44, v46, v44
	v_cvt_pk_bf16_f32 v44, v44, v97
	ds_read_u16 v46, v52 offset:1088
	ds_write_b16 v52, v44 offset:1360
	v_mov_b32_e32 v167, v178
	v_mov_b32_e32 v178, v157
	s_waitcnt lgkmcnt(1)
	v_lshlrev_b32_e32 v46, 16, v46
	v_mul_f32_e32 v51, 0x3d372713, v46
	v_mul_f32_e32 v51, v51, v46
	v_fma_f32 v51, v51, v46, v46
	v_mul_f32_e32 v51, 0x3fcc422a, v51
	v_mul_f32_e32 v51, 0xbfb8aa3b, v51
	v_exp_f32_e32 v51, v51
	s_nop 0
	v_add_f32_e32 v44, 1.0, v51
	v_rcp_f32_e32 v44, v44
	v_add_f32_e32 v51, v194, v68
	v_mul_f32_e32 v46, v51, v46
	v_mov_b32_e32 v194, v168
	v_mul_f32_e32 v44, v46, v44
	v_cvt_pk_bf16_f32 v44, v44, v97
	ds_read_u16 v46, v52 offset:816
	ds_write_b16 v52, v44 offset:1088
	v_mov_b32_e32 v168, v177
	v_mov_b32_e32 v177, v158
	s_waitcnt lgkmcnt(1)
	v_lshlrev_b32_e32 v46, 16, v46
	v_mul_f32_e32 v51, 0x3d372713, v46
	v_mul_f32_e32 v51, v51, v46
	v_fma_f32 v51, v51, v46, v46
	v_mul_f32_e32 v51, 0x3fcc422a, v51
	v_mul_f32_e32 v51, 0xbfb8aa3b, v51
	v_exp_f32_e32 v51, v51
	v_mul_f32_e32 v46, v47, v46
	v_add_f32_e32 v44, 1.0, v51
	v_rcp_f32_e32 v44, v44
	s_nop 0
	v_mul_f32_e32 v44, v46, v44
	v_cvt_pk_bf16_f32 v44, v44, v97
	ds_read_u16 v46, v52 offset:544
	ds_write_b16 v52, v44 offset:816
	s_waitcnt lgkmcnt(1)
	v_lshlrev_b32_e32 v46, 16, v46
	v_mul_f32_e32 v47, 0x3d372713, v46
	v_mul_f32_e32 v47, v47, v46
	v_fma_f32 v47, v47, v46, v46
	v_mul_f32_e32 v47, 0x3fcc422a, v47
	v_mul_f32_e32 v47, 0xbfb8aa3b, v47
	v_exp_f32_e32 v47, v47
	v_mul_f32_e32 v39, v39, v46
	v_add_f32_e32 v44, 1.0, v47
	v_rcp_f32_e32 v44, v44
	s_nop 0
	v_mul_f32_e32 v39, v39, v44
	v_cvt_pk_bf16_f32 v39, v39, v97
	ds_read_u16 v44, v52 offset:272
	ds_write_b16 v52, v39 offset:544
	s_waitcnt lgkmcnt(1)
	v_lshlrev_b32_e32 v44, 16, v44
	v_mul_f32_e32 v46, 0x3d372713, v44
	v_mul_f32_e32 v46, v46, v44
	v_fma_f32 v46, v46, v44, v44
	v_mul_f32_e32 v46, 0x3fcc422a, v46
	v_mul_f32_e32 v46, 0xbfb8aa3b, v46
	v_exp_f32_e32 v46, v46
	v_mul_f32_e32 v42, v42, v44
	v_add_f32_e32 v39, 1.0, v46
	v_rcp_f32_e32 v39, v39
	s_nop 0
	v_mul_f32_e32 v39, v42, v39
	v_cvt_pk_bf16_f32 v42, v39, v97
	ds_read_u16 v44, v52
	ds_bpermute_b32 v39, v140, v36
	ds_write_b16 v52, v42 offset:272
	s_waitcnt lgkmcnt(2)
	v_lshlrev_b32_e32 v36, 16, v44
	v_mul_f32_e32 v44, 0x3d372713, v36
	v_mul_f32_e32 v44, v44, v36
	v_fma_f32 v44, v44, v36, v36
	v_mul_f32_e32 v44, 0x3fcc422a, v44
	v_mul_f32_e32 v44, 0xbfb8aa3b, v44
	v_exp_f32_e32 v44, v44
	v_mul_f32_e32 v36, v37, v36
	v_add_f32_e32 v37, v43, v76
	v_add_f32_e32 v42, 1.0, v44
	v_rcp_f32_e32 v42, v42
	s_nop 0
	v_mul_f32_e32 v36, v36, v42
	v_cvt_pk_bf16_f32 v36, v36, v97
	ds_write_b16 v52, v36
	v_mul_f32_e32 v36, v41, v49
	s_waitcnt lgkmcnt(2)
	v_pk_mul_f32 v[36:37], v[36:37], v[38:39]
	s_nop 0
	v_mul_f32_e32 v36, v36, v39
	v_add_f32_e32 v37, v37, v45
	v_fmac_f32_e32 v37, v127, v36
	v_mov_b32_e32 v127, v37
	s_cbranch_scc0 .LBB0_698
.LBB0_746:
	s_mov_b32 s100, 0xbfb8aa3b
	v_mul_f32_e32 v211, 0xbfb8aa3b, v125
	v_mul_f32_e32 v241, 0xbfb8aa3b, v204
	v_bitop3_b32 v36, s2, v95, v141 bitop3:0xde
	v_mul_lo_u32 v36, v36, s50
	v_add_u32_e32 v206, v107, v36
	ds_read_b128 v[212:215], v206
	ds_read_b128 v[216:219], v206 offset:64
	ds_read_b128 v[220:223], v206 offset:128
	ds_read_b128 v[224:227], v206 offset:192
	ds_read_b128 v[228:231], v206 offset:4352
	ds_read_b128 v[232:235], v206 offset:4416
	ds_read_b128 v[236:239], v206 offset:4480
	ds_read_b128 v[244:247], v206 offset:4544
	ds_read_b128 v[248:251], v206 offset:8704
	ds_read_b128 v[252:255], v206 offset:8768
	s_mov_b32 s30, s28
	s_mov_b32 s31, s28
	s_mov_b32 s29, s28
	v_mov_b64_e32 v[38:39], s[30:31]
	s_and_b64 vcc, exec, s[8:9]
	v_mov_b64_e32 v[36:37], s[28:29]
	s_waitcnt lgkmcnt(9)
	v_mfma_f32_16x16x32_bf16 v[44:47], v[212:215], v[32:35], 0
	v_mfma_f32_16x16x32_bf16 v[48:51], v[212:215], v[20:23], 0
	s_cbranch_vccnz .LBB0_748
	v_mfma_f32_16x16x32_bf16 v[36:39], v[212:215], v[0:3], 0

; #define LAS __attribute__((address_space(3)))
; __device__ __forceinline__ float fsig(float x) { return __builtin_amdgcn_rcpf(1.0f + __expf(-x)); }
; template <bool PASS2>
; __device__ __forceinline__ void lru_item(const Frame& F, const Args& a, int item) {
;     ...
;             if (PASS2 && dir == 0) {
; #pragma unroll
;                 for (int i1 = 0; i1 < 4; ++i1)
; #pragma unroll
;                     for (int i2 = 0; i2 < 4; ++i2) { hf[0][i1][i2] = hf[1][i1][i2]; hf[1][i1][i2] = hf[2][i1][i2]; hf[2][i1][i2] = hf[3][i1][i2]; } }
;             f32x4 ar[4], ai[4], ax[4];
; #pragma unroll
;             for (int rt = 0; rt < 4; ++rt) { ar[rt] = (f32x4){0.f, 0.f, 0.f, 0.f}; ai[rt] = (f32x4){0.f, 0.f, 0.f, 0.f}; ax[rt] = (f32x4){0.f, 0.f, 0.f, 0.f};
; #pragma unroll
;                 for (int ks = 0; ks < 4; ++ks) { const bf16x8 xf = *(const LAS bf16x8*)(AT + (64 * s + 16 * rt + fr) * AT_PITCH + 64 * ks + 16 * fq);
;                     ar[rt] = __builtin_amdgcn_mfma_f32_16x16x32_bf16(xf, wrf[ks], ar[rt], 0, 0, 0); ai[rt] = __builtin_amdgcn_mfma_f32_16x16x32_bf16(xf, wif[ks], ai[rt], 0, 0, 0);
;                     if (ks == ks0) ax[rt] = __builtin_amdgcn_mfma_f32_16x16x32_bf16(xf, sel, ax[rt], 0, 0, 0); } }
;             const int tl0 = 64 * s + 16 * fq;
;             float A16 = 1.f, B16 = 0.f;
; #pragma unroll
;             for (int e = 0; e < 16; ++e) { const int ee = dir ? 15 - e : e; const int rt = ee >> 2, j = ee & 3;
;                 const float rg = fsig(ar[rt][j] + ba), ig = fsig(ai[rt][j] + bi); const float la = logu * rg; const float av = __expf(la);
.LBB0_827:
	s_mov_b32 s100, 0xbfb8aa3b
	v_mul_f32_e32 v211, 0xbfb8aa3b, v204
	v_mul_f32_e32 v241, 0xbfb8aa3b, v206
	v_add_u32_e32 v125, v209, v103
	v_add_u32_e32 v240, 0x11400, v125
	ds_read_b128 v[212:215], v240
	ds_read_b128 v[216:219], v240 offset:64
	ds_read_b128 v[220:223], v240 offset:128
	ds_read_b128 v[224:227], v240 offset:192
	ds_read_b128 v[228:231], v240 offset:4352
	ds_read_b128 v[232:235], v240 offset:4416
	ds_read_b128 v[236:239], v240 offset:4480
	ds_read_b128 v[244:247], v240 offset:4544
	ds_read_b128 v[248:251], v240 offset:8704
	ds_read_b128 v[252:255], v240 offset:8768
	v_mov_b32_e32 v182, v36
	v_mov_b32_e32 v179, v39
	v_mov_b32_e32 v180, v38
	v_mov_b32_e32 v181, v37
	v_mov_b32_e32 v174, v44
	v_cndmask_b32_e64 v44, 0, 1, s[2:3]
	v_mov_b32_e32 v173, v45
	v_mov_b32_e32 v175, v43
	v_mov_b32_e32 v176, v42
	v_mov_b32_e32 v177, v41
	v_mov_b32_e32 v178, v40
	s_waitcnt lgkmcnt(9)
	v_mfma_f32_16x16x32_bf16 v[40:43], v[212:215], v[4:7], 0
	v_cmp_ne_u32_e64 s[8:9], 1, v44
	s_mov_b32 s30, s28
	s_mov_b32 s31, s28
	v_mfma_f32_16x16x32_bf16 v[44:47], v[212:215], v[12:15], 0
	s_mov_b32 s29, s28
	v_mov_b64_e32 v[62:63], s[30:31]
	v_mov_b32_e32 v183, v132
	v_mov_b32_e32 v184, v131
	v_mov_b32_e32 v185, v146
	v_mov_b32_e32 v186, v143
	v_mov_b32_e32 v187, v142
	v_mov_b32_e32 v188, v133
	v_mov_b32_e32 v132, v198
	v_mov_b32_e32 v131, v200
	v_mov_b32_e32 v146, v202
	v_mov_b32_e32 v143, v203
	v_mov_b32_e32 v142, v205
	v_mov_b32_e32 v133, v124
	v_mov_b64_e32 v[60:61], s[28:29]
	s_andn2_b64 vcc, exec, s[2:3]
	s_cbranch_vccnz .LBB0_829
	v_mfma_f32_16x16x32_bf16 v[60:63], v[212:215], v[0:3], 0

; __device__ __forceinline__ float fsig(float x) { return __builtin_amdgcn_rcpf(1.0f + __expf(-x)); }
; template <bool PASS2>
; __device__ __forceinline__ void lru_item(const Frame& F, const Args& a, int item) {
;     ...
;             for (int e = 0; e < 16; ++e) { const int ee = dir ? 15 - e : e; const int rt = ee >> 2, j = ee & 3;
;                 const float rg = fsig(ar[rt][j] + ba), ig = fsig(ai[rt][j] + bi); const float la = logu * rg; const float av = __expf(la);
;                 const float mult = (t0 + tl0 + ee == tstart) ? 1.0f : __builtin_amdgcn_sqrtf(fmaxf(1.0f - av * av, 0.f)); const float bv = mult * ig * ax[rt][j];
;                 ar[rt][j] = av; ai[rt][j] = bv; B16 = av * B16 + bv; A16 = av * A16; }
.LBB0_859:
	v_fma_f32 v80, v80, s100, v211
	v_exp_f32_e32 v80, v80
	v_fma_f32 v81, v81, s100, v211
	v_exp_f32_e32 v81, v81
	v_add_f32_e32 v80, 1.0, v80
	v_rcp_f32_e32 v80, v80
	v_add_f32_e32 v81, 1.0, v81
	v_rcp_f32_e32 v81, v81
	v_mul_f32_e32 v80, v207, v80
	v_mul_f32_e32 v80, 0x3fb8aa3b, v80
	v_exp_f32_e32 v80, v80
	v_mul_f32_e32 v81, v207, v81
	v_fma_f32 v76, v76, s100, v241
	v_fma_f32 v85, -v80, v80, 1.0
	v_max_f32_e32 v85, 0, v85
	v_mul_f32_e32 v81, 0x3fb8aa3b, v81
	v_exp_f32_e32 v76, v76
	v_sqrt_f32_e32 v85, v85
	v_fma_f32 v77, v77, s100, v241
	v_exp_f32_e32 v81, v81
	v_exp_f32_e32 v77, v77
	v_add_u32_e32 v84, s82, v208
	v_cmp_ne_u32_e32 vcc, 0, v84
	v_add_f32_e32 v76, 1.0, v76
	v_rcp_f32_e32 v76, v76
	v_cndmask_b32_e32 v84, 1.0, v85, vcc
	v_fma_f32 v85, -v81, v81, 1.0
	v_add_f32_e32 v77, 1.0, v77
	v_max_f32_e32 v85, 0, v85
	v_rcp_f32_e32 v77, v77
	v_sqrt_f32_e32 v85, v85
	v_mul_f32_e32 v76, v76, v84
	v_mul_f32_e32 v189, v76, v60
	v_mul_f32_e32 v76, v77, v85
	v_mul_f32_e32 v190, v76, v61
	v_fma_f32 v61, v82, s100, v211
	v_exp_f32_e32 v61, v61
	v_add_f32_e32 v76, v206, v78
	v_fma_f32 v78, v83, s100, v211
	v_add_f32_e32 v61, 1.0, v61
	v_rcp_f32_e32 v61, v61
	v_exp_f32_e32 v78, v78
	v_mul_f32_e32 v76, 0xbfb8aa3b, v76
	v_exp_f32_e32 v76, v76
	v_mul_f32_e32 v61, v207, v61
	v_mul_f32_e32 v61, 0x3fb8aa3b, v61
	v_add_f32_e32 v78, 1.0, v78
	v_exp_f32_e32 v61, v61
	v_rcp_f32_e32 v78, v78
	v_add_f32_e32 v76, 1.0, v76
	v_rcp_f32_e32 v76, v76
	v_fma_f32 v82, -v61, v61, 1.0
	v_mul_f32_e32 v78, v207, v78
	v_max_f32_e32 v82, 0, v82
	v_mul_f32_e32 v78, 0x3fb8aa3b, v78
	v_sqrt_f32_e32 v82, v82
	v_fma_f32 v79, v79, s100, v241
	v_exp_f32_e32 v78, v78
	v_exp_f32_e32 v79, v79
	v_mul_f32_e32 v76, v76, v82
	v_mul_f32_e32 v191, v76, v62
	v_fma_f32 v82, -v78, v78, 1.0
	v_add_f32_e32 v79, 1.0, v79
	v_max_f32_e32 v82, 0, v82
	v_rcp_f32_e32 v79, v79
	v_sqrt_f32_e32 v82, v82
	v_fma_f32 v68, v68, s100, v241
	v_exp_f32_e32 v68, v68
	v_mul_f32_e32 v76, v79, v82
	v_mul_f32_e32 v193, v76, v63
	v_fma_f32 v63, v72, s100, v211
	v_exp_f32_e32 v63, v63
	v_fma_f32 v72, v73, s100, v211
	v_exp_f32_e32 v72, v72
	v_add_f32_e32 v63, 1.0, v63
	v_rcp_f32_e32 v63, v63
	v_add_f32_e32 v68, 1.0, v68
	v_add_f32_e32 v72, 1.0, v72
	v_rcp_f32_e32 v72, v72
	v_mul_f32_e32 v63, v207, v63
	v_mul_f32_e32 v63, 0x3fb8aa3b, v63
	v_exp_f32_e32 v63, v63
	v_mul_f32_e32 v72, v207, v72
	v_mul_f32_e32 v72, 0x3fb8aa3b, v72
	v_fma_f32 v73, -v63, v63, 1.0
	v_max_f32_e32 v73, 0, v73
	v_rcp_f32_e32 v68, v68
	v_sqrt_f32_e32 v73, v73
	v_fma_f32 v69, v69, s100, v241
	v_exp_f32_e32 v72, v72
	v_exp_f32_e32 v69, v69
	v_mul_f32_e32 v68, v68, v73
	v_fma_f32 v60, 0, v80, v189
	v_fma_f32 v73, -v72, v72, 1.0
	v_add_f32_e32 v69, 1.0, v69
	v_max_f32_e32 v73, 0, v73
	v_rcp_f32_e32 v69, v69
	v_sqrt_f32_e32 v73, v73
	v_fma_f32 v60, v81, v60, v190
	v_mul_f32_e32 v77, v80, v81
	v_fma_f32 v60, v61, v60, v191
	v_mul_f32_e32 v62, v61, v77
	v_fma_f32 v60, v78, v60, v193
	v_mul_f32_e32 v62, v78, v62
	v_mul_f32_e32 v194, v68, v52
	v_fma_f32 v52, v60, v63, v194
	v_mul_f32_e32 v60, v62, v63
	v_mul_f32_e32 v62, v69, v73
	v_mul_f32_e32 v195, v62, v53
	v_fma_f32 v53, v74, s100, v211
	v_exp_f32_e32 v53, v53
	v_fma_f32 v68, v75, s100, v211
	v_exp_f32_e32 v68, v68
	v_add_f32_e32 v53, 1.0, v53
	v_rcp_f32_e32 v53, v53
	v_add_f32_e32 v68, 1.0, v68
	v_fma_f32 v62, v70, s100, v241
	v_mul_f32_e32 v53, v207, v53
	v_mul_f32_e32 v53, 0x3fb8aa3b, v53
	v_exp_f32_e32 v53, v53
	v_rcp_f32_e32 v68, v68
	v_exp_f32_e32 v62, v62
	v_fma_f32 v69, -v53, v53, 1.0
	v_mul_f32_e32 v68, v207, v68
	v_add_f32_e32 v62, 1.0, v62
	v_max_f32_e32 v69, 0, v69
	v_fma_f32 v70, v71, s100, v241
	v_mul_f32_e32 v68, 0x3fb8aa3b, v68
	v_rcp_f32_e32 v62, v62
	v_sqrt_f32_e32 v69, v69
	v_exp_f32_e32 v70, v70
	v_exp_f32_e32 v68, v68
	v_mul_f32_e32 v60, v72, v60
	v_mul_f32_e32 v62, v62, v69
	v_add_f32_e32 v69, 1.0, v70
	v_fma_f32 v70, -v68, v68, 1.0
	v_max_f32_e32 v70, 0, v70
	v_rcp_f32_e32 v69, v69
	v_sqrt_f32_e32 v70, v70
	v_mul_f32_e32 v196, v62, v54
	v_mul_f32_e32 v54, v53, v60
	v_mul_f32_e32 v60, v69, v70
	v_mul_f32_e32 v197, v60, v55
	v_fma_f32 v55, v64, s100, v211
	v_exp_f32_e32 v55, v55
	v_fma_f32 v60, v65, s100, v211
	v_exp_f32_e32 v60, v60
	v_add_f32_e32 v55, 1.0, v55
	v_rcp_f32_e32 v55, v55
	v_fma_f32 v56, v56, s100, v241
	v_add_f32_e32 v60, 1.0, v60
	v_rcp_f32_e32 v60, v60
	v_mul_f32_e32 v55, v207, v55
	v_mul_f32_e32 v55, 0x3fb8aa3b, v55
	v_exp_f32_e32 v55, v55
	v_exp_f32_e32 v56, v56
	v_mul_f32_e32 v60, v207, v60
	v_fma_f32 v62, -v55, v55, 1.0
	v_add_f32_e32 v56, 1.0, v56
	v_max_f32_e32 v62, 0, v62
	v_mul_f32_e32 v60, 0x3fb8aa3b, v60
	v_rcp_f32_e32 v56, v56
	v_sqrt_f32_e32 v62, v62
	v_fma_f32 v57, v57, s100, v241
	v_exp_f32_e32 v60, v60
	v_exp_f32_e32 v57, v57
	v_mul_f32_e32 v56, v56, v62
	v_fma_f32 v52, v72, v52, v195
	v_fma_f32 v62, -v60, v60, 1.0
	v_add_f32_e32 v57, 1.0, v57
	v_max_f32_e32 v62, 0, v62
	v_rcp_f32_e32 v57, v57
	v_sqrt_f32_e32 v62, v62
	v_fma_f32 v52, v53, v52, v196
	v_fma_f32 v52, v68, v52, v197
	v_mul_f32_e32 v54, v68, v54
	v_mul_f32_e32 v199, v56, v40
	v_fma_f32 v40, v52, v55, v199
	v_mul_f32_e32 v52, v54, v55
	v_mul_f32_e32 v54, v57, v62
	v_mul_f32_e32 v201, v54, v41
	v_fma_f32 v41, v66, s100, v211
	v_exp_f32_e32 v41, v41
	v_fma_f32 v54, v58, s100, v241
	v_exp_f32_e32 v54, v54
	v_add_f32_e32 v41, 1.0, v41
	v_rcp_f32_e32 v41, v41
	v_add_f32_e32 v54, 1.0, v54
	v_rcp_f32_e32 v54, v54
	v_mul_f32_e32 v41, v207, v41
	v_mul_f32_e32 v41, 0x3fb8aa3b, v41
	v_exp_f32_e32 v56, v41
	v_fma_f32 v41, v67, s100, v211
	v_exp_f32_e32 v41, v41
; #define LAS __attribute__((address_space(3)))
; __device__ __forceinline__ unsigned cvt_pk_bf16(float lo, float hi) { unsigned r; asm volatile("v_cvt_pk_bf16_f32 %0, %1, %2" : "=v"(r) : "v"(lo), "v"(hi)); return r; }
; __device__ __forceinline__ float bf2f(unsigned short b) { return __uint_as_float(((unsigned)b) << 16); }
; __device__ __forceinline__ float fsig(float x) { return __builtin_amdgcn_rcpf(1.0f + __expf(-x)); }
; template <bool PASS2>
; __device__ __forceinline__ void lru_item(const Frame& F, const Args& a, int item) {
;     ...
;             for (int e = 0; e < 16; ++e) { const int ee = dir ? 15 - e : e; const int rt = ee >> 2, j = ee & 3;
;                 const float rg = fsig(ar[rt][j] + ba), ig = fsig(ai[rt][j] + bi); const float la = logu * rg; const float av = __expf(la);
;                 const float mult = (t0 + tl0 + ee == tstart) ? 1.0f : __builtin_amdgcn_sqrtf(fmaxf(1.0f - av * av, 0.f)); const float bv = mult * ig * ax[rt][j];
;                 ar[rt][j] = av; ai[rt][j] = bv; B16 = av * B16 + bv; A16 = av * A16; }
;             const int pos = dir ? 3 - fq : fq;
;             float PA = 1.f, PB = 0.f, QA = 1.f, QB = 0.f;
; #pragma unroll
;             for (int i = 0; i < 4; ++i) { const int k = dir ? 3 - i : i; const float Ak = __shfl(A16, fr + 16 * k), Bk = __shfl(B16, fr + 16 * k);
;                 if (i < pos) { PB = Ak * PB + Bk; PA = Ak * PA; }
;                 QB = Ak * QB + Bk; QA = Ak * QA; }
;             if (PASS2) {
;                 float h = PA * hc + PB;
; #pragma unroll
;                 for (int e = 0; e < 16; ++e) { const int ee = dir ? 15 - e : e; const int rt = ee >> 2, j = ee & 3; h = ar[rt][j] * h + ai[rt][j];
;                     if (dir == 0) hf[3][rt][j] = h;
;                     else { LAS unsigned short* yp = (LAS unsigned short*)(R0 + (tl0 + ee) * AT_PITCH + 2 * c); const float yb = bf2f(*yp);
;                         const float u2 = 1.5957691216057308f * (yb + 0.044715f * yb * yb * yb);
;                         const float y = (hf[3][rt][j] + h) * yb * fsig(u2);
;                         *yp = (unsigned short)(cvt_pk_bf16(y, 0.f) & 0xffffu); } }
;                 hc = QA * hc + QB;
;             } else { TB = QA * TB + QB; TA = QA * TA; }
	v_fma_f32 v57, -v56, v56, 1.0
	v_max_f32_e32 v57, 0, v57
	v_sqrt_f32_e32 v57, v57
	v_add_f32_e32 v41, 1.0, v41
	v_rcp_f32_e32 v41, v41
	v_fma_f32 v58, v59, s100, v241
	v_exp_f32_e32 v58, v58
	v_mul_f32_e32 v41, v207, v41
	v_mul_f32_e32 v41, 0x3fb8aa3b, v41
	v_exp_f32_e32 v59, v41
	v_mul_f32_e32 v41, v54, v57
	v_add_f32_e32 v54, 1.0, v58
	v_rcp_f32_e32 v54, v54
	v_fma_f32 v57, -v59, v59, 1.0
	v_max_f32_e32 v57, 0, v57
	v_sqrt_f32_e32 v57, v57
	v_mul_f32_e32 v198, v41, v42
	v_fma_f32 v45, v45, s100, v241
	v_exp_f32_e32 v45, v45
	v_mul_f32_e32 v42, v54, v57
	v_mul_f32_e32 v200, v42, v43
	v_fma_f32 v42, v48, s100, v211
	v_exp_f32_e32 v42, v42
	v_add_f32_e32 v43, v206, v44
	v_fma_f32 v44, v49, s100, v211
	v_add_f32_e32 v42, 1.0, v42
	v_rcp_f32_e32 v42, v42
	v_exp_f32_e32 v44, v44
	v_mul_f32_e32 v43, 0xbfb8aa3b, v43
	v_exp_f32_e32 v43, v43
	v_mul_f32_e32 v42, v207, v42
	v_mul_f32_e32 v42, 0x3fb8aa3b, v42
	v_add_f32_e32 v44, 1.0, v44
	v_exp_f32_e32 v42, v42
	v_rcp_f32_e32 v44, v44
	v_add_f32_e32 v43, 1.0, v43
	v_rcp_f32_e32 v43, v43
	v_fma_f32 v48, -v42, v42, 1.0
	v_mul_f32_e32 v44, v207, v44
	v_max_f32_e32 v48, 0, v48
	v_mul_f32_e32 v44, 0x3fb8aa3b, v44
	v_sqrt_f32_e32 v48, v48
	v_exp_f32_e32 v44, v44
	v_add_f32_e32 v45, 1.0, v45
	v_rcp_f32_e32 v45, v45
	v_mul_f32_e32 v43, v43, v48
	v_fma_f32 v48, -v44, v44, 1.0
	v_max_f32_e32 v48, 0, v48
	v_sqrt_f32_e32 v48, v48
	v_fma_f32 v40, v60, v40, v201
	v_mul_f32_e32 v52, v60, v52
	v_fma_f32 v40, v56, v40, v198
	v_mul_f32_e32 v41, v56, v52
	v_fma_f32 v40, v59, v40, v200
	v_mul_f32_e32 v41, v59, v41
	v_mul_f32_e32 v202, v43, v36
	v_fma_f32 v36, v40, v42, v202
	v_mul_f32_e32 v40, v41, v42
	v_mul_f32_e32 v41, v45, v48
	v_mul_f32_e32 v203, v41, v37
	v_fma_f32 v37, v50, s100, v211
	v_exp_f32_e32 v37, v37
	v_fma_f32 v41, v46, s100, v241
	v_exp_f32_e32 v41, v41
	v_add_f32_e32 v37, 1.0, v37
	v_rcp_f32_e32 v37, v37
	v_add_f32_e32 v41, 1.0, v41
	v_fma_f32 v46, v47, s100, v241
	v_mul_f32_e32 v37, v207, v37
	v_mul_f32_e32 v37, 0x3fb8aa3b, v37
	v_exp_f32_e32 v43, v37
	v_fma_f32 v37, v51, s100, v211
	v_exp_f32_e32 v37, v37
	v_fma_f32 v45, -v43, v43, 1.0
	v_max_f32_e32 v45, 0, v45
	v_rcp_f32_e32 v41, v41
	v_add_f32_e32 v37, 1.0, v37
	v_rcp_f32_e32 v37, v37
	v_sqrt_f32_e32 v45, v45
	v_exp_f32_e32 v46, v46
	v_fma_f32 v36, v44, v36, v203
	v_mul_f32_e32 v37, v207, v37
	v_mul_f32_e32 v37, 0x3fb8aa3b, v37
	v_exp_f32_e32 v37, v37
	v_mul_f32_e32 v41, v41, v45
	v_add_f32_e32 v45, 1.0, v46
	v_rcp_f32_e32 v45, v45
	v_fma_f32 v46, -v37, v37, 1.0
	v_max_f32_e32 v46, 0, v46
	v_sqrt_f32_e32 v46, v46
	v_mul_f32_e32 v40, v44, v40
	v_mul_f32_e32 v205, v41, v38
	v_fma_f32 v41, v43, v36, v205
	v_mul_f32_e32 v47, v43, v40
	v_mul_f32_e32 v40, v45, v46
	v_mov_b32_e32 v36, v39
	v_pk_mul_f32 v[124:125], v[40:41], v[36:37]
	s_add_i32 s82, s82, 64
	v_pk_fma_f32 v[38:39], v[40:41], v[36:37], v[124:125] op_sel:[0,0,1] op_sel_hi:[1,1,0]
	v_mul_f32_e32 v36, v37, v47
	ds_bpermute_b32 v39, v139, v36
	ds_bpermute_b32 v45, v139, v38
	ds_bpermute_b32 v48, v128, v36
	ds_bpermute_b32 v49, v128, v38
	ds_bpermute_b32 v40, v129, v36
	ds_bpermute_b32 v50, v129, v38
	s_waitcnt lgkmcnt(4)
	v_fmac_f32_e32 v45, 0, v39
	v_cndmask_b32_e64 v46, v39, 1.0, s[0:1]
	v_cndmask_b32_e64 v47, v45, 0, s[0:1]
	ds_bpermute_b32 v41, v130, v36
	s_waitcnt lgkmcnt(3)
	v_fma_f32 v36, v47, v48, v49
	v_mul_f32_e32 v51, v46, v48
	v_cndmask_b32_e64 v46, v46, v51, s[16:17]
	v_cndmask_b32_e64 v36, v47, v36, s[16:17]
	v_fmac_f32_e32 v49, v45, v48
	s_waitcnt lgkmcnt(1)
	v_fma_f32 v45, v36, v40, v50
	v_mul_f32_e32 v47, v46, v40
	v_cndmask_b32_e64 v46, v46, v47, s[4:5]
	v_cndmask_b32_e64 v36, v36, v45, s[4:5]
	v_fmac_f32_e32 v36, v210, v46
	v_fmac_f32_e32 v189, v80, v36
	v_fmac_f32_e32 v190, v81, v189
	v_fmac_f32_e32 v191, v61, v190
	v_fmac_f32_e32 v193, v78, v191
	v_fmac_f32_e32 v194, v63, v193
	v_fmac_f32_e32 v195, v72, v194
	v_fmac_f32_e32 v196, v53, v195
	v_fmac_f32_e32 v197, v68, v196
	v_fmac_f32_e32 v199, v55, v197
	v_fmac_f32_e32 v201, v60, v199
	v_fmac_f32_e32 v198, v56, v201
	v_fmac_f32_e32 v200, v59, v198
	ds_bpermute_b32 v38, v130, v38
	v_fmac_f32_e32 v202, v42, v200
	v_fmac_f32_e32 v203, v44, v202
	v_mul_f32_e32 v45, v49, v40
	v_fmac_f32_e32 v205, v43, v203
	v_fmac_f32_e32 v124, v37, v205
	v_mul_f32_e32 v36, v39, v48
	v_add_f32_e32 v37, v45, v50
	s_waitcnt lgkmcnt(1)
	v_pk_mul_f32 v[36:37], v[36:37], v[40:41]
	s_cmpk_lg_i32 s82, 0x100
	v_mul_f32_e32 v36, v36, v41
	s_waitcnt lgkmcnt(0)
	v_add_f32_e32 v46, v37, v38
	v_fmac_f32_e32 v46, v210, v36
	v_add_u32_e32 v209, 0x4400, v209
	s_cbranch_scc0 .LBB0_861
	v_mov_b32_e32 v36, v163
	v_mov_b32_e32 v37, v164
	v_mov_b32_e32 v38, v165
	v_mov_b32_e32 v39, v166
	v_mov_b32_e32 v40, v167
	v_mov_b32_e32 v41, v168
	v_mov_b32_e32 v42, v169
	v_mov_b32_e32 v43, v170
	v_mov_b32_e32 v44, v171
	v_mov_b32_e32 v45, v172
	v_mov_b32_e32 v147, v188
	v_mov_b32_e32 v148, v187
	v_mov_b32_e32 v149, v186
	v_mov_b32_e32 v150, v185
	v_mov_b32_e32 v151, v184
	v_mov_b32_e32 v152, v183
	v_mov_b32_e32 v153, v182
	v_mov_b32_e32 v154, v181
	v_mov_b32_e32 v155, v180
	v_mov_b32_e32 v156, v179
	v_mov_b32_e32 v157, v178
	v_mov_b32_e32 v158, v177
	v_mov_b32_e32 v159, v176
	v_mov_b32_e32 v160, v175
	v_mov_b32_e32 v161, v174
	v_mov_b32_e32 v162, v173
	v_mov_b32_e32 v163, v201
	v_mov_b32_e32 v164, v199
	v_mov_b32_e32 v165, v197
	v_mov_b32_e32 v166, v196
	v_mov_b32_e32 v167, v195
	v_mov_b32_e32 v168, v194
	v_mov_b32_e32 v169, v193
	v_mov_b32_e32 v170, v191
	v_mov_b32_e32 v171, v190
	v_mov_b32_e32 v172, v189
	v_mov_b32_e32 v210, v46
	s_branch .LBB0_827

; __device__ __forceinline__ float fsig(float x) { return __builtin_amdgcn_rcpf(1.0f + __expf(-x)); }
; template <bool PASS2>
; __device__ __forceinline__ void lru_item(const Frame& F, const Args& a, int item) {
;     ...
;             for (int e = 0; e < 16; ++e) { const int ee = dir ? 15 - e : e; const int rt = ee >> 2, j = ee & 3;
;                 const float rg = fsig(ar[rt][j] + ba), ig = fsig(ai[rt][j] + bi); const float la = logu * rg; const float av = __expf(la);
;                 const float mult = (t0 + tl0 + ee == tstart) ? 1.0f : __builtin_amdgcn_sqrtf(fmaxf(1.0f - av * av, 0.f)); const float bv = mult * ig * ax[rt][j];
;                 ar[rt][j] = av; ai[rt][j] = bv; B16 = av * B16 + bv; A16 = av * A16; }
.LBB0_864:
	s_nop 3
	v_fma_f32 v83, v83, s100, v211
	v_exp_f32_e32 v83, v83
	v_fma_f32 v79, v79, s100, v241
	v_exp_f32_e32 v79, v79
	v_add_f32_e32 v83, 1.0, v83
	v_rcp_f32_e32 v83, v83
	s_xor_b32 s29, s46, 0xc0
	v_add_f32_e32 v79, 1.0, v79
	v_mul_f32_e32 v83, v126, v83
	v_mul_f32_e32 v83, 0x3fb8aa3b, v83
	v_exp_f32_e32 v83, v83
	v_or_b32_e32 v84, s29, v103
	v_fma_f32 v82, v82, s100, v211
	v_rcp_f32_e32 v79, v79
	v_fma_f32 v86, -v83, v83, 1.0
	v_max_f32_e32 v86, 0, v86
	v_sqrt_f32_e32 v86, v86
	v_add_u32_e32 v85, s79, v84
	v_exp_f32_e32 v82, v82
	v_cmp_ne_u32_e32 vcc, s76, v85
	v_fma_f32 v81, v81, s100, v211
	v_cndmask_b32_e32 v85, 1.0, v86, vcc
	v_mul_f32_e32 v79, v79, v85
	v_mul_f32_e32 v75, v79, v75
	v_add_f32_e32 v79, 1.0, v82
	v_rcp_f32_e32 v79, v79
	v_exp_f32_e32 v81, v81
	v_fma_f32 v78, v78, s100, v241
	v_mul_f32_e32 v79, v126, v79
	v_mul_f32_e32 v79, 0x3fb8aa3b, v79
	v_add_f32_e32 v81, 1.0, v81
	v_exp_f32_e32 v79, v79
	v_rcp_f32_e32 v81, v81
	v_exp_f32_e32 v78, v78
	v_fma_f32 v85, -v79, v79, 1.0
	v_mul_f32_e32 v81, v126, v81
	v_add_f32_e32 v78, 1.0, v78
	v_max_f32_e32 v85, 0, v85
	v_mul_f32_e32 v81, 0x3fb8aa3b, v81
	v_rcp_f32_e32 v78, v78
	v_sqrt_f32_e32 v85, v85
	v_fma_f32 v77, v77, s100, v241
	v_exp_f32_e32 v81, v81
	v_exp_f32_e32 v77, v77
	v_mul_f32_e32 v78, v78, v85
	v_fma_f32 v82, 0, v83, v75
	v_fma_f32 v85, -v81, v81, 1.0
	v_add_f32_e32 v77, 1.0, v77
	v_max_f32_e32 v85, 0, v85
	v_rcp_f32_e32 v77, v77
	v_sqrt_f32_e32 v85, v85
	v_mul_f32_e32 v74, v78, v74
	v_fma_f32 v78, v79, v82, v74
	v_mul_f32_e32 v77, v77, v85
	v_mul_f32_e32 v73, v77, v73
	v_fma_f32 v77, v81, v78, v73
	v_fma_f32 v78, v80, s100, v211
	v_exp_f32_e32 v78, v78
	v_fma_f32 v71, v71, s100, v211
	v_exp_f32_e32 v71, v71
	v_add_f32_e32 v78, 1.0, v78
	v_rcp_f32_e32 v78, v78
	v_add_f32_e32 v71, 1.0, v71
	v_fma_f32 v76, v76, s100, v241
	v_rcp_f32_e32 v71, v71
	v_mul_f32_e32 v78, v126, v78
	v_mul_f32_e32 v78, 0x3fb8aa3b, v78
	v_exp_f32_e32 v78, v78
	v_exp_f32_e32 v76, v76
	v_fma_f32 v70, v70, s100, v211
	v_mul_f32_e32 v82, v83, v79
	v_exp_f32_e32 v70, v70
	v_mul_f32_e32 v80, v81, v82
	v_fma_f32 v82, -v78, v78, 1.0
	v_mul_f32_e32 v71, v126, v71
	v_add_f32_e32 v76, 1.0, v76
	v_max_f32_e32 v82, 0, v82
	v_mul_f32_e32 v71, 0x3fb8aa3b, v71
	v_rcp_f32_e32 v76, v76
	v_sqrt_f32_e32 v82, v82
	v_fma_f32 v67, v67, s100, v241
	v_exp_f32_e32 v71, v71
	v_exp_f32_e32 v67, v67
	v_add_f32_e32 v70, 1.0, v70
	v_rcp_f32_e32 v70, v70
	v_fma_f32 v69, v69, s100, v211
	v_exp_f32_e32 v69, v69
	v_mul_f32_e32 v76, v76, v82
	v_fma_f32 v82, -v71, v71, 1.0
	v_add_f32_e32 v67, 1.0, v67
	v_max_f32_e32 v82, 0, v82
	v_rcp_f32_e32 v67, v67
	v_sqrt_f32_e32 v82, v82
	v_mul_f32_e32 v70, v126, v70
	v_mul_f32_e32 v70, 0x3fb8aa3b, v70
	v_add_f32_e32 v69, 1.0, v69
	v_fma_f32 v66, v66, s100, v241
	v_exp_f32_e32 v70, v70
	v_rcp_f32_e32 v69, v69
	v_exp_f32_e32 v66, v66
	v_mul_f32_e32 v72, v76, v72
	v_mul_f32_e32 v67, v67, v82
	v_fma_f32 v76, v78, v77, v72
	v_mul_f32_e32 v77, v78, v80
	v_mul_f32_e32 v63, v67, v63
	v_fma_f32 v67, v71, v76, v63
	v_mul_f32_e32 v76, v71, v77
	v_fma_f32 v77, -v70, v70, 1.0
	v_mul_f32_e32 v69, v126, v69
	v_add_f32_e32 v66, 1.0, v66
	v_max_f32_e32 v77, 0, v77
	v_mul_f32_e32 v69, 0x3fb8aa3b, v69
	v_rcp_f32_e32 v66, v66
	v_sqrt_f32_e32 v77, v77
	v_fma_f32 v65, v65, s100, v241
	v_exp_f32_e32 v69, v69
	v_exp_f32_e32 v65, v65
	v_mul_f32_e32 v66, v66, v77
	v_mul_f32_e32 v62, v66, v62
	v_fma_f32 v77, -v69, v69, 1.0
	v_add_f32_e32 v65, 1.0, v65
	v_max_f32_e32 v77, 0, v77
	v_rcp_f32_e32 v65, v65
	v_sqrt_f32_e32 v77, v77
	v_fma_f32 v66, v70, v67, v62
	v_fma_f32 v59, v59, s100, v211
	v_mul_f32_e32 v65, v65, v77
	v_mul_f32_e32 v61, v65, v61
	v_fma_f32 v65, v69, v66, v61
	v_fma_f32 v66, v68, s100, v211
	v_exp_f32_e32 v66, v66
	v_exp_f32_e32 v59, v59
	v_fma_f32 v64, v64, s100, v241
	v_add_f32_e32 v66, 1.0, v66
	v_rcp_f32_e32 v66, v66
	v_add_f32_e32 v59, 1.0, v59
	v_rcp_f32_e32 v59, v59
	v_exp_f32_e32 v64, v64
	v_mul_f32_e32 v66, v126, v66
	v_mul_f32_e32 v66, 0x3fb8aa3b, v66
	v_exp_f32_e32 v66, v66
	v_mul_f32_e32 v59, v126, v59
	v_add_f32_e32 v64, 1.0, v64
	v_fma_f32 v68, -v66, v66, 1.0
	v_max_f32_e32 v68, 0, v68
	v_mul_f32_e32 v59, 0x3fb8aa3b, v59
	v_rcp_f32_e32 v64, v64
	v_sqrt_f32_e32 v68, v68
	v_fma_f32 v55, v55, s100, v241
	v_exp_f32_e32 v59, v59
	v_exp_f32_e32 v55, v55
	v_mul_f32_e32 v64, v64, v68
	v_mul_f32_e32 v67, v70, v76
	v_fma_f32 v68, -v59, v59, 1.0
	v_add_f32_e32 v55, 1.0, v55
	v_max_f32_e32 v68, 0, v68
	v_rcp_f32_e32 v55, v55
	v_sqrt_f32_e32 v68, v68
	v_mul_f32_e32 v67, v69, v67
	v_mul_f32_e32 v60, v64, v60
	v_fma_f32 v64, v66, v65, v60
	v_mul_f32_e32 v55, v55, v68
	v_mul_f32_e32 v65, v66, v67
	v_mul_f32_e32 v67, v55, v51
	v_fma_f32 v55, v58, s100, v211
	v_exp_f32_e32 v55, v55
	v_fma_f32 v51, v59, v64, v67
	v_fma_f32 v54, v54, s100, v241
	v_add_f32_e32 v55, 1.0, v55
	v_rcp_f32_e32 v55, v55
	v_exp_f32_e32 v54, v54
	v_mul_f32_e32 v58, v59, v65
	v_mul_f32_e32 v55, v126, v55
	v_mul_f32_e32 v55, 0x3fb8aa3b, v55
	v_exp_f32_e32 v64, v55
	v_fma_f32 v55, v57, s100, v211
	v_exp_f32_e32 v55, v55
	v_fma_f32 v53, v53, s100, v241
	v_exp_f32_e32 v53, v53
	v_fma_f32 v57, -v64, v64, 1.0
	v_add_f32_e32 v55, 1.0, v55
	v_rcp_f32_e32 v55, v55
	v_add_f32_e32 v54, 1.0, v54
	v_max_f32_e32 v57, 0, v57
	v_rcp_f32_e32 v54, v54
	v_mul_f32_e32 v55, v126, v55
	v_mul_f32_e32 v55, 0x3fb8aa3b, v55
	v_exp_f32_e32 v65, v55
	v_sqrt_f32_e32 v57, v57
	v_add_f32_e32 v53, 1.0, v53
	v_rcp_f32_e32 v53, v53
	v_fma_f32 v55, -v65, v65, 1.0
	v_max_f32_e32 v55, 0, v55
	v_sqrt_f32_e32 v55, v55
	v_mul_f32_e32 v54, v54, v57
	v_mul_f32_e32 v57, v54, v50
	v_fma_f32 v50, v64, v51, v57
	v_mul_f32_e32 v53, v53, v55
	v_mul_f32_e32 v51, v64, v58
; #define LAS __attribute__((address_space(3)))
; __device__ __forceinline__ unsigned cvt_pk_bf16(float lo, float hi) { unsigned r; asm volatile("v_cvt_pk_bf16_f32 %0, %1, %2" : "=v"(r) : "v"(lo), "v"(hi)); return r; }
; __device__ __forceinline__ float bf2f(unsigned short b) { return __uint_as_float(((unsigned)b) << 16); }
; __device__ __forceinline__ float fsig(float x) { return __builtin_amdgcn_rcpf(1.0f + __expf(-x)); }
; template <bool PASS2>
; __device__ __forceinline__ void lru_item(const Frame& F, const Args& a, int item) {
;     ...
;             for (int e = 0; e < 16; ++e) { const int ee = dir ? 15 - e : e; const int rt = ee >> 2, j = ee & 3;
;                 const float rg = fsig(ar[rt][j] + ba), ig = fsig(ai[rt][j] + bi); const float la = logu * rg; const float av = __expf(la);
;                 const float mult = (t0 + tl0 + ee == tstart) ? 1.0f : __builtin_amdgcn_sqrtf(fmaxf(1.0f - av * av, 0.f)); const float bv = mult * ig * ax[rt][j];
;                 ar[rt][j] = av; ai[rt][j] = bv; B16 = av * B16 + bv; A16 = av * A16; }
;             const int pos = dir ? 3 - fq : fq;
;             float PA = 1.f, PB = 0.f, QA = 1.f, QB = 0.f;
; #pragma unroll
;             for (int i = 0; i < 4; ++i) { const int k = dir ? 3 - i : i; const float Ak = __shfl(A16, fr + 16 * k), Bk = __shfl(B16, fr + 16 * k);
;                 if (i < pos) { PB = Ak * PB + Bk; PA = Ak * PA; }
;                 QB = Ak * QB + Bk; QA = Ak * QA; }
;             if (PASS2) {
;                 float h = PA * hc + PB;
; #pragma unroll
;                 for (int e = 0; e < 16; ++e) { const int ee = dir ? 15 - e : e; const int rt = ee >> 2, j = ee & 3; h = ar[rt][j] * h + ai[rt][j];
;                     if (dir == 0) hf[3][rt][j] = h;
;                     else { LAS unsigned short* yp = (LAS unsigned short*)(R0 + (tl0 + ee) * AT_PITCH + 2 * c); const float yb = bf2f(*yp);
;                         const float u2 = 1.5957691216057308f * (yb + 0.044715f * yb * yb * yb);
;                         const float y = (hf[3][rt][j] + h) * yb * fsig(u2);
;                         *yp = (unsigned short)(cvt_pk_bf16(y, 0.f) & 0xffffu); } }
	v_mul_f32_e32 v58, v53, v49
	v_fma_f32 v49, v65, v50, v58
	v_fma_f32 v50, v56, s100, v211
	v_exp_f32_e32 v50, v50
	v_fma_f32 v47, v47, s100, v211
	v_exp_f32_e32 v47, v47
	v_add_f32_e32 v50, 1.0, v50
	v_rcp_f32_e32 v50, v50
	v_add_f32_e32 v47, 1.0, v47
	v_fma_f32 v52, v52, s100, v241
	v_mul_f32_e32 v50, v126, v50
	v_mul_f32_e32 v50, 0x3fb8aa3b, v50
	v_exp_f32_e32 v56, v50
	v_rcp_f32_e32 v47, v47
	v_exp_f32_e32 v52, v52
	v_mul_f32_e32 v53, v65, v51
	v_fma_f32 v50, -v56, v56, 1.0
	v_mul_f32_e32 v47, v126, v47
	v_add_f32_e32 v51, 1.0, v52
	v_max_f32_e32 v50, 0, v50
	v_mul_f32_e32 v47, 0x3fb8aa3b, v47
	v_rcp_f32_e32 v51, v51
	v_sqrt_f32_e32 v50, v50
	v_fma_f32 v43, v43, s100, v241
	v_exp_f32_e32 v47, v47
	v_exp_f32_e32 v43, v43
	v_mul_f32_e32 v50, v51, v50
	v_mul_f32_e32 v68, v50, v48
	v_fma_f32 v51, -v47, v47, 1.0
	v_add_f32_e32 v43, 1.0, v43
	v_max_f32_e32 v51, 0, v51
	v_rcp_f32_e32 v43, v43
	v_sqrt_f32_e32 v52, v51
	v_fma_f32 v42, v42, s100, v241
	v_exp_f32_e32 v42, v42
	v_mul_f32_e32 v50, v43, v52
	v_fma_f32 v43, v46, s100, v211
	v_exp_f32_e32 v43, v43
	v_mov_b32_e32 v46, v39
	v_add_f32_e32 v42, 1.0, v42
	v_rcp_f32_e32 v42, v42
	v_add_f32_e32 v39, 1.0, v43
	v_rcp_f32_e32 v39, v39
	v_fma_f32 v51, v56, v49, v68
	v_fma_f32 v45, v45, s100, v211
	v_mul_f32_e32 v39, v126, v39
	v_mul_f32_e32 v39, 0x3fb8aa3b, v39
	v_exp_f32_e32 v39, v39
	v_pk_mul_f32 v[48:49], v[50:51], v[46:47]
	v_exp_f32_e32 v45, v45
	v_pk_fma_f32 v[50:51], v[50:51], v[46:47], v[48:49] op_sel_hi:[1,1,0]
	v_fma_f32 v43, -v39, v39, 1.0
	v_max_f32_e32 v43, 0, v43
	v_sqrt_f32_e32 v43, v43
	v_mul_f32_e32 v53, v56, v53
	v_mul_f32_e32 v46, v47, v53
	v_mul_f32_e32 v50, v42, v43
	v_pk_mul_f32 v[42:43], v[50:51], v[38:39]
	v_fma_f32 v44, v44, s100, v211
	v_pk_fma_f32 v[50:51], v[50:51], v[38:39], v[42:43] op_sel_hi:[1,1,0]
	v_add_f32_e32 v38, 1.0, v45
	v_rcp_f32_e32 v38, v38
	v_fma_f32 v41, v41, s100, v241
	v_exp_f32_e32 v41, v41
	v_mul_f32_e32 v38, v126, v38
	v_mul_f32_e32 v38, 0x3fb8aa3b, v38
	v_exp_f32_e32 v45, v38
	v_mul_f32_e32 v38, v39, v46
	v_exp_f32_e32 v46, v44
	v_mov_b32_e32 v44, v37
	v_fma_f32 v43, -v45, v45, 1.0
	v_add_f32_e32 v37, 1.0, v46
	v_rcp_f32_e32 v37, v37
	v_fma_f32 v40, v40, s100, v241
	v_add_f32_e32 v41, 1.0, v41
	v_max_f32_e32 v43, 0, v43
	v_mul_f32_e32 v37, v126, v37
	v_exp_f32_e32 v40, v40
	v_mul_f32_e32 v37, 0x3fb8aa3b, v37
	v_rcp_f32_e32 v41, v41
	v_sqrt_f32_e32 v43, v43
	v_exp_f32_e32 v37, v37
	v_add_f32_e32 v40, 1.0, v40
	v_mul_f32_e32 v38, v45, v38
	v_mul_f32_e32 v50, v41, v43
	v_rcp_f32_e32 v43, v40
	v_fma_f32 v40, -v37, v37, 1.0
	v_max_f32_e32 v40, 0, v40
	v_sqrt_f32_e32 v46, v40
	v_pk_mul_f32 v[40:41], v[50:51], v[44:45]
	s_add_i32 s46, s46, 64
	v_pk_fma_f32 v[52:53], v[50:51], v[44:45], v[40:41] op_sel_hi:[1,1,0]
	s_cmpk_lg_i32 s46, 0x100
	v_mul_f32_e32 v52, v43, v46
	v_pk_mul_f32 v[50:51], v[52:53], v[36:37]
	s_nop 0
	v_pk_fma_f32 v[54:55], v[52:53], v[36:37], v[50:51] op_sel:[0,0,1] op_sel_hi:[1,1,0]
	v_mad_u64_u32 v[52:53], s[30:31], v84, s33, v[120:121]
	v_mul_f32_e32 v36, v37, v38
	ds_read_u16 v38, v52 offset:4080
	ds_bpermute_b32 v41, v130, v36
	ds_bpermute_b32 v43, v130, v54
	ds_bpermute_b32 v49, v129, v36
	ds_bpermute_b32 v55, v129, v54
	s_waitcnt lgkmcnt(4)
	v_lshlrev_b32_e32 v51, 16, v38
	v_mul_f32_e32 v38, 0x3d372713, v51
	v_mul_f32_e32 v38, v38, v51
	v_fma_f32 v38, v38, v51, v51
	v_mul_f32_e32 v38, 0x3fcc422a, v38
	v_mul_f32_e32 v38, 0xbfb8aa3b, v38
	v_exp_f32_e32 v53, v38
	ds_bpermute_b32 v38, v128, v36
	ds_bpermute_b32 v76, v128, v54
	s_waitcnt lgkmcnt(4)
	v_fmac_f32_e32 v43, 0, v41
	v_cndmask_b32_e64 v44, v41, 1.0, s[4:5]
	v_cndmask_b32_e64 v46, v43, 0, s[4:5]
	s_waitcnt lgkmcnt(2)
	v_fma_f32 v77, v46, v49, v55
	v_mul_f32_e32 v80, v44, v49
	v_cndmask_b32_e64 v44, v44, v80, s[6:7]
	v_cndmask_b32_e64 v46, v46, v77, s[6:7]
	s_waitcnt lgkmcnt(0)
	v_fma_f32 v77, v46, v38, v76
	v_mul_f32_e32 v80, v44, v38
	v_add_f32_e32 v53, 1.0, v53
	v_cndmask_b32_e64 v44, v44, v80, s[0:1]
	v_cndmask_b32_e64 v46, v46, v77, s[0:1]
	v_rcp_f32_e32 v53, v53
	v_fmac_f32_e32 v46, v127, v44
	v_fmac_f32_e32 v75, v83, v46
	v_add_f32_e32 v44, v124, v75
	v_mul_f32_e32 v44, v44, v51
	v_mul_f32_e32 v44, v44, v53
	v_cvt_pk_bf16_f32 v44, v44, v97
	ds_read_u16 v46, v52 offset:3808
	ds_write_b16 v52, v44 offset:4080
	v_fmac_f32_e32 v74, v79, v75
	v_fmac_f32_e32 v73, v81, v74
	v_fmac_f32_e32 v72, v78, v73
	s_waitcnt lgkmcnt(1)
	v_lshlrev_b32_e32 v46, 16, v46
	v_mul_f32_e32 v51, 0x3d372713, v46
	v_mul_f32_e32 v51, v51, v46
	v_fma_f32 v51, v51, v46, v46
	v_mul_f32_e32 v51, 0x3fcc422a, v51
	v_mul_f32_e32 v51, 0xbfb8aa3b, v51
	v_exp_f32_e32 v51, v51
	v_fmac_f32_e32 v63, v71, v72
	v_fmac_f32_e32 v62, v70, v63
	v_fmac_f32_e32 v61, v69, v62
	v_add_f32_e32 v44, 1.0, v51
	v_rcp_f32_e32 v44, v44
	v_add_f32_e32 v51, v205, v74
	v_mul_f32_e32 v46, v51, v46
	v_fmac_f32_e32 v60, v66, v61
	v_mul_f32_e32 v44, v46, v44
	v_cvt_pk_bf16_f32 v44, v44, v97
	ds_read_u16 v46, v52 offset:3536
	ds_write_b16 v52, v44 offset:3808
	v_fmac_f32_e32 v67, v59, v60
	v_fmac_f32_e32 v57, v64, v67
	v_fmac_f32_e32 v58, v65, v57
	s_waitcnt lgkmcnt(1)
	v_lshlrev_b32_e32 v46, 16, v46
	v_mul_f32_e32 v51, 0x3d372713, v46
	v_mul_f32_e32 v51, v51, v46
	v_fma_f32 v51, v51, v46, v46
	v_mul_f32_e32 v51, 0x3fcc422a, v51
	v_mul_f32_e32 v51, 0xbfb8aa3b, v51
	v_exp_f32_e32 v51, v51
	v_fmac_f32_e32 v68, v56, v58
	v_fmac_f32_e32 v48, v47, v68
	v_add_f32_e32 v47, v193, v48
	v_add_f32_e32 v44, 1.0, v51
	v_rcp_f32_e32 v44, v44
	v_add_f32_e32 v51, v203, v73
	v_mul_f32_e32 v46, v51, v46
	v_fmac_f32_e32 v42, v39, v48
	v_mul_f32_e32 v44, v46, v44
	v_cvt_pk_bf16_f32 v44, v44, v97
	ds_read_u16 v46, v52 offset:3264
	ds_write_b16 v52, v44 offset:3536
	v_add_f32_e32 v39, v191, v42
	v_fmac_f32_e32 v40, v45, v42
	v_add_f32_e32 v42, v190, v40
	s_waitcnt lgkmcnt(1)
; #define LAS __attribute__((address_space(3)))
; __device__ __forceinline__ unsigned cvt_pk_bf16(float lo, float hi) { unsigned r; asm volatile("v_cvt_pk_bf16_f32 %0, %1, %2" : "=v"(r) : "v"(lo), "v"(hi)); return r; }
; __device__ __forceinline__ float bf2f(unsigned short b) { return __uint_as_float(((unsigned)b) << 16); }
; __device__ __forceinline__ float fsig(float x) { return __builtin_amdgcn_rcpf(1.0f + __expf(-x)); }
; template <bool PASS2>
; __device__ __forceinline__ void lru_item(const Frame& F, const Args& a, int item) {
;     ...
;                 for (int e = 0; e < 16; ++e) { const int ee = dir ? 15 - e : e; const int rt = ee >> 2, j = ee & 3; h = ar[rt][j] * h + ai[rt][j];
;                     if (dir == 0) hf[3][rt][j] = h;
;                     else { LAS unsigned short* yp = (LAS unsigned short*)(R0 + (tl0 + ee) * AT_PITCH + 2 * c); const float yb = bf2f(*yp);
;                         const float u2 = 1.5957691216057308f * (yb + 0.044715f * yb * yb * yb);
;                         const float y = (hf[3][rt][j] + h) * yb * fsig(u2);
;                         *yp = (unsigned short)(cvt_pk_bf16(y, 0.f) & 0xffffu); } }
;                 hc = QA * hc + QB;
;             } else { TB = QA * TB + QB; TA = QA * TA; }
;             if (PASS2 && dir == 1) {
; #pragma unroll
;                 for (int i1 = 0; i1 < 4; ++i1)
; #pragma unroll
;                     for (int i2 = 0; i2 < 4; ++i2) { hf[3][i1][i2] = hf[2][i1][i2]; hf[2][i1][i2] = hf[1][i1][i2]; hf[1][i1][i2] = hf[0][i1][i2]; } }
	v_lshlrev_b32_e32 v46, 16, v46
	v_mul_f32_e32 v51, 0x3d372713, v46
	v_mul_f32_e32 v51, v51, v46
	v_fma_f32 v51, v51, v46, v46
	v_mul_f32_e32 v51, 0x3fcc422a, v51
	v_mul_f32_e32 v51, 0xbfb8aa3b, v51
	v_exp_f32_e32 v51, v51
	v_fmac_f32_e32 v50, v37, v40
	v_add_f32_e32 v37, v189, v50
	ds_bpermute_b32 v45, v139, v54
	v_add_f32_e32 v44, 1.0, v51
	v_rcp_f32_e32 v44, v44
	v_add_f32_e32 v51, v202, v72
	v_mul_f32_e32 v46, v51, v46
	v_fmac_f32_e32 v55, v43, v49
	v_mul_f32_e32 v44, v46, v44
	v_cvt_pk_bf16_f32 v44, v44, v97
	ds_read_u16 v46, v52 offset:2992
	ds_write_b16 v52, v44 offset:3264
	v_mul_f32_e32 v43, v55, v38
	v_mov_b32_e32 v124, v133
	v_mov_b32_e32 v205, v142
	s_waitcnt lgkmcnt(1)
	v_lshlrev_b32_e32 v46, 16, v46
	v_mul_f32_e32 v51, 0x3d372713, v46
	v_mul_f32_e32 v51, v51, v46
	v_fma_f32 v51, v51, v46, v46
	v_mul_f32_e32 v51, 0x3fcc422a, v51
	v_mul_f32_e32 v51, 0xbfb8aa3b, v51
	v_exp_f32_e32 v51, v51
	v_mov_b32_e32 v203, v143
	v_mov_b32_e32 v202, v146
	v_mov_b32_e32 v193, v169
	v_add_f32_e32 v44, 1.0, v51
	v_rcp_f32_e32 v44, v44
	v_add_f32_e32 v51, v200, v63
	v_mul_f32_e32 v46, v51, v46
	v_mov_b32_e32 v200, v131
	v_mul_f32_e32 v44, v46, v44
	v_cvt_pk_bf16_f32 v44, v44, v97
	ds_read_u16 v46, v52 offset:2720
	ds_write_b16 v52, v44 offset:2992
	v_mov_b32_e32 v191, v170
	v_mov_b32_e32 v190, v171
	v_mov_b32_e32 v189, v172
	s_waitcnt lgkmcnt(1)
	v_lshlrev_b32_e32 v46, 16, v46
	v_mul_f32_e32 v51, 0x3d372713, v46
	v_mul_f32_e32 v51, v51, v46
	v_fma_f32 v51, v51, v46, v46
	v_mul_f32_e32 v51, 0x3fcc422a, v51
	v_mul_f32_e32 v51, 0xbfb8aa3b, v51
	v_exp_f32_e32 v51, v51
	v_mov_b32_e32 v133, v188
	v_mov_b32_e32 v142, v187
	v_mov_b32_e32 v143, v186
	v_add_f32_e32 v44, 1.0, v51
	v_rcp_f32_e32 v44, v44
	v_add_f32_e32 v51, v198, v62
	v_mul_f32_e32 v46, v51, v46
	v_mov_b32_e32 v198, v132
	v_mul_f32_e32 v44, v46, v44
	v_cvt_pk_bf16_f32 v44, v44, v97
	ds_read_u16 v46, v52 offset:2448
	ds_write_b16 v52, v44 offset:2720
	v_mov_b32_e32 v146, v185
	v_mov_b32_e32 v131, v184
	v_mov_b32_e32 v132, v183
	s_waitcnt lgkmcnt(1)
	v_lshlrev_b32_e32 v46, 16, v46
	v_mul_f32_e32 v51, 0x3d372713, v46
	v_mul_f32_e32 v51, v51, v46
	v_fma_f32 v51, v51, v46, v46
	v_mul_f32_e32 v51, 0x3fcc422a, v51
	v_mul_f32_e32 v51, 0xbfb8aa3b, v51
	v_exp_f32_e32 v51, v51
	v_mov_b32_e32 v169, v176
	v_mov_b32_e32 v170, v175
	v_mov_b32_e32 v171, v174
	v_add_f32_e32 v44, 1.0, v51
	v_rcp_f32_e32 v44, v44
	v_add_f32_e32 v51, v201, v61
	v_mul_f32_e32 v46, v51, v46
	v_mov_b32_e32 v201, v163
	v_mul_f32_e32 v44, v46, v44
	v_cvt_pk_bf16_f32 v44, v44, v97
	ds_read_u16 v46, v52 offset:2176
	ds_write_b16 v52, v44 offset:2448
	v_mov_b32_e32 v163, v182
	v_mov_b32_e32 v172, v173
	v_mov_b32_e32 v188, v147
	s_waitcnt lgkmcnt(1)
	v_lshlrev_b32_e32 v46, 16, v46
	v_mul_f32_e32 v51, 0x3d372713, v46
	v_mul_f32_e32 v51, v51, v46
	v_fma_f32 v51, v51, v46, v46
	v_mul_f32_e32 v51, 0x3fcc422a, v51
	v_mul_f32_e32 v51, 0xbfb8aa3b, v51
	v_exp_f32_e32 v51, v51
	v_mov_b32_e32 v187, v148
	v_mov_b32_e32 v186, v149
	v_mov_b32_e32 v185, v150
	v_add_f32_e32 v44, 1.0, v51
	v_rcp_f32_e32 v44, v44
	v_add_f32_e32 v51, v199, v60
	v_mul_f32_e32 v46, v51, v46
	v_mov_b32_e32 v199, v164
	v_mul_f32_e32 v44, v46, v44
	v_cvt_pk_bf16_f32 v44, v44, v97
	ds_read_u16 v46, v52 offset:1904
	ds_write_b16 v52, v44 offset:2176
	v_mov_b32_e32 v164, v181
	v_mov_b32_e32 v184, v151
	v_mov_b32_e32 v183, v152
	s_waitcnt lgkmcnt(1)
	v_lshlrev_b32_e32 v46, 16, v46
	v_mul_f32_e32 v51, 0x3d372713, v46
	v_mul_f32_e32 v51, v51, v46
	v_fma_f32 v51, v51, v46, v46
	v_mul_f32_e32 v51, 0x3fcc422a, v51
	v_mul_f32_e32 v51, 0xbfb8aa3b, v51
	v_exp_f32_e32 v51, v51
	v_mov_b32_e32 v182, v153
	v_mov_b32_e32 v181, v154
	v_mov_b32_e32 v176, v159
	v_add_f32_e32 v44, 1.0, v51
	v_rcp_f32_e32 v44, v44
	v_add_f32_e32 v51, v197, v67
	v_mul_f32_e32 v46, v51, v46
	v_mov_b32_e32 v197, v165
	v_mul_f32_e32 v44, v46, v44
	v_cvt_pk_bf16_f32 v44, v44, v97
	ds_read_u16 v46, v52 offset:1632
	ds_write_b16 v52, v44 offset:1904
	v_mov_b32_e32 v165, v180
	v_mov_b32_e32 v180, v155
	v_mov_b32_e32 v175, v160
	s_waitcnt lgkmcnt(1)
	v_lshlrev_b32_e32 v46, 16, v46
	v_mul_f32_e32 v51, 0x3d372713, v46
	v_mul_f32_e32 v51, v51, v46
	v_fma_f32 v51, v51, v46, v46
	v_mul_f32_e32 v51, 0x3fcc422a, v51
	v_mul_f32_e32 v51, 0xbfb8aa3b, v51
	v_exp_f32_e32 v51, v51
	v_mov_b32_e32 v174, v161
	v_mov_b32_e32 v173, v162
	v_add_f32_e32 v44, 1.0, v51
	v_rcp_f32_e32 v44, v44
	v_add_f32_e32 v51, v196, v57
	v_mul_f32_e32 v46, v51, v46
	v_mov_b32_e32 v196, v166
	v_mul_f32_e32 v44, v46, v44
	v_cvt_pk_bf16_f32 v44, v44, v97
	ds_read_u16 v46, v52 offset:1360
	ds_write_b16 v52, v44 offset:1632
	v_mov_b32_e32 v166, v179
	v_mov_b32_e32 v179, v156
	s_waitcnt lgkmcnt(1)
; #define LAS __attribute__((address_space(3)))
; __device__ __forceinline__ unsigned cvt_pk_bf16(float lo, float hi) { unsigned r; asm volatile("v_cvt_pk_bf16_f32 %0, %1, %2" : "=v"(r) : "v"(lo), "v"(hi)); return r; }
; __device__ __forceinline__ float bf2f(unsigned short b) { return __uint_as_float(((unsigned)b) << 16); }
; __device__ __forceinline__ float fsig(float x) { return __builtin_amdgcn_rcpf(1.0f + __expf(-x)); }
; template <bool PASS2>
; __device__ __forceinline__ void lru_item(const Frame& F, const Args& a, int item) {
;     ...
;                 for (int ks = 0; ks < 4; ++ks) { const bf16x8 xf = *(const LAS bf16x8*)(AT + (64 * s + 16 * rt + fr) * AT_PITCH + 64 * ks + 16 * fq);
;                     ar[rt] = __builtin_amdgcn_mfma_f32_16x16x32_bf16(xf, wrf[ks], ar[rt], 0, 0, 0); ai[rt] = __builtin_amdgcn_mfma_f32_16x16x32_bf16(xf, wif[ks], ai[rt], 0, 0, 0);
;                     if (ks == ks0) ax[rt] = __builtin_amdgcn_mfma_f32_16x16x32_bf16(xf, sel, ax[rt], 0, 0, 0); } }
;             const int tl0 = 64 * s + 16 * fq;
;             float A16 = 1.f, B16 = 0.f;
; #pragma unroll
;             for (int e = 0; e < 16; ++e) { const int ee = dir ? 15 - e : e; const int rt = ee >> 2, j = ee & 3;
;                 const float rg = fsig(ar[rt][j] + ba), ig = fsig(ai[rt][j] + bi); const float la = logu * rg; const float av = __expf(la);
;     ...
;                 for (int e = 0; e < 16; ++e) { const int ee = dir ? 15 - e : e; const int rt = ee >> 2, j = ee & 3; h = ar[rt][j] * h + ai[rt][j];
;                     if (dir == 0) hf[3][rt][j] = h;
;                     else { LAS unsigned short* yp = (LAS unsigned short*)(R0 + (tl0 + ee) * AT_PITCH + 2 * c); const float yb = bf2f(*yp);
;                         const float u2 = 1.5957691216057308f * (yb + 0.044715f * yb * yb * yb);
;                         const float y = (hf[3][rt][j] + h) * yb * fsig(u2);
;                         *yp = (unsigned short)(cvt_pk_bf16(y, 0.f) & 0xffffu); } }
;                 hc = QA * hc + QB;
;             } else { TB = QA * TB + QB; TA = QA * TA; }
;             if (PASS2 && dir == 1) {
; #pragma unroll
;                 for (int i1 = 0; i1 < 4; ++i1)
; #pragma unroll
;                     for (int i2 = 0; i2 < 4; ++i2) { hf[3][i1][i2] = hf[2][i1][i2]; hf[2][i1][i2] = hf[1][i1][i2]; hf[1][i1][i2] = hf[0][i1][i2]; } }
	v_lshlrev_b32_e32 v46, 16, v46
	v_mul_f32_e32 v51, 0x3d372713, v46
	v_mul_f32_e32 v51, v51, v46
	v_fma_f32 v51, v51, v46, v46
	v_mul_f32_e32 v51, 0x3fcc422a, v51
	v_mul_f32_e32 v51, 0xbfb8aa3b, v51
	v_exp_f32_e32 v51, v51
	s_nop 0
	v_add_f32_e32 v44, 1.0, v51
	v_rcp_f32_e32 v44, v44
	v_add_f32_e32 v51, v195, v58
	v_mul_f32_e32 v46, v51, v46
	v_mov_b32_e32 v195, v167
	v_mul_f32_e32 v44, v46, v44
	v_cvt_pk_bf16_f32 v44, v44, v97
	ds_read_u16 v46, v52 offset:1088
	ds_write_b16 v52, v44 offset:1360
	v_mov_b32_e32 v167, v178
	v_mov_b32_e32 v178, v157
	s_waitcnt lgkmcnt(1)
	v_lshlrev_b32_e32 v46, 16, v46
	v_mul_f32_e32 v51, 0x3d372713, v46
	v_mul_f32_e32 v51, v51, v46
	v_fma_f32 v51, v51, v46, v46
	v_mul_f32_e32 v51, 0x3fcc422a, v51
	v_mul_f32_e32 v51, 0xbfb8aa3b, v51
	v_exp_f32_e32 v51, v51
	s_nop 0
	v_add_f32_e32 v44, 1.0, v51
	v_rcp_f32_e32 v44, v44
	v_add_f32_e32 v51, v194, v68
	v_mul_f32_e32 v46, v51, v46
	v_mov_b32_e32 v194, v168
	v_mul_f32_e32 v44, v46, v44
	v_cvt_pk_bf16_f32 v44, v44, v97
	ds_read_u16 v46, v52 offset:816
	ds_write_b16 v52, v44 offset:1088
	v_mov_b32_e32 v168, v177
	v_mov_b32_e32 v177, v158
	s_waitcnt lgkmcnt(1)
	v_lshlrev_b32_e32 v46, 16, v46
	v_mul_f32_e32 v51, 0x3d372713, v46
	v_mul_f32_e32 v51, v51, v46
	v_fma_f32 v51, v51, v46, v46
	v_mul_f32_e32 v51, 0x3fcc422a, v51
	v_mul_f32_e32 v51, 0xbfb8aa3b, v51
	v_exp_f32_e32 v51, v51
	v_mul_f32_e32 v46, v47, v46
	v_add_f32_e32 v44, 1.0, v51
	v_rcp_f32_e32 v44, v44
	s_nop 0
	v_mul_f32_e32 v44, v46, v44
	v_cvt_pk_bf16_f32 v44, v44, v97
	ds_read_u16 v46, v52 offset:544
	ds_write_b16 v52, v44 offset:816
	s_waitcnt lgkmcnt(1)
	v_lshlrev_b32_e32 v46, 16, v46
	v_mul_f32_e32 v47, 0x3d372713, v46
	v_mul_f32_e32 v47, v47, v46
	v_fma_f32 v47, v47, v46, v46
	v_mul_f32_e32 v47, 0x3fcc422a, v47
	v_mul_f32_e32 v47, 0xbfb8aa3b, v47
	v_exp_f32_e32 v47, v47
	v_mul_f32_e32 v39, v39, v46
	v_add_f32_e32 v44, 1.0, v47
	v_rcp_f32_e32 v44, v44
	s_nop 0
	v_mul_f32_e32 v39, v39, v44
	v_cvt_pk_bf16_f32 v39, v39, v97
	ds_read_u16 v44, v52 offset:272
	ds_write_b16 v52, v39 offset:544
	s_waitcnt lgkmcnt(1)
	v_lshlrev_b32_e32 v44, 16, v44
	v_mul_f32_e32 v46, 0x3d372713, v44
	v_mul_f32_e32 v46, v46, v44
	v_fma_f32 v46, v46, v44, v44
	v_mul_f32_e32 v46, 0x3fcc422a, v46
	v_mul_f32_e32 v46, 0xbfb8aa3b, v46
	v_exp_f32_e32 v46, v46
	v_mul_f32_e32 v42, v42, v44
	v_add_f32_e32 v39, 1.0, v46
	v_rcp_f32_e32 v39, v39
	s_nop 0
	v_mul_f32_e32 v39, v42, v39
	v_cvt_pk_bf16_f32 v42, v39, v97
	ds_read_u16 v44, v52
	ds_bpermute_b32 v39, v139, v36
	ds_write_b16 v52, v42 offset:272
	s_waitcnt lgkmcnt(2)
	v_lshlrev_b32_e32 v36, 16, v44
	v_mul_f32_e32 v44, 0x3d372713, v36
	v_mul_f32_e32 v44, v44, v36
	v_fma_f32 v44, v44, v36, v36
	v_mul_f32_e32 v44, 0x3fcc422a, v44
	v_mul_f32_e32 v44, 0xbfb8aa3b, v44
	v_exp_f32_e32 v44, v44
	v_mul_f32_e32 v36, v37, v36
	v_add_f32_e32 v37, v43, v76
	v_add_f32_e32 v42, 1.0, v44
	v_rcp_f32_e32 v42, v42
	s_nop 0
	v_mul_f32_e32 v36, v36, v42
	v_cvt_pk_bf16_f32 v36, v36, v97
	ds_write_b16 v52, v36
	v_mul_f32_e32 v36, v41, v49
	s_waitcnt lgkmcnt(2)
	v_pk_mul_f32 v[36:37], v[36:37], v[38:39]
	s_nop 0
	v_mul_f32_e32 v36, v36, v39
	v_add_f32_e32 v37, v37, v45
	v_fmac_f32_e32 v37, v127, v36
	v_mov_b32_e32 v127, v37
	s_cbranch_scc0 .LBB0_817
.LBB0_865:
	s_mov_b32 s100, 0xbfb8aa3b
	v_mul_f32_e32 v211, 0xbfb8aa3b, v125
	v_mul_f32_e32 v241, 0xbfb8aa3b, v204
	v_bitop3_b32 v36, s46, v145, v140 bitop3:0xde
	v_mul_lo_u32 v36, v36, s33
	v_add_u32_e32 v206, v105, v36
	ds_read_b128 v[212:215], v206
	ds_read_b128 v[216:219], v206 offset:64
	ds_read_b128 v[220:223], v206 offset:128
	ds_read_b128 v[224:227], v206 offset:192
	ds_read_b128 v[228:231], v206 offset:4352
	ds_read_b128 v[232:235], v206 offset:4416
	ds_read_b128 v[236:239], v206 offset:4480
	ds_read_b128 v[244:247], v206 offset:4544
	ds_read_b128 v[248:251], v206 offset:8704
	ds_read_b128 v[252:255], v206 offset:8768
	s_mov_b32 s30, s28
	s_mov_b32 s31, s28
	s_mov_b32 s29, s28
	v_mov_b64_e32 v[38:39], s[30:31]
	s_and_b64 vcc, exec, s[8:9]
	v_mov_b64_e32 v[36:37], s[28:29]
	s_waitcnt lgkmcnt(9)
	v_mfma_f32_16x16x32_bf16 v[44:47], v[212:215], v[32:35], 0
	v_mfma_f32_16x16x32_bf16 v[48:51], v[212:215], v[20:23], 0
	s_cbranch_vccnz .LBB0_867
	v_mfma_f32_16x16x32_bf16 v[36:39], v[212:215], v[0:3], 0
